# GEMM MFMA blocks (P1/P3/P4/P5): the 20 mid-block 's_setprio 0; s_setprio 1' toggle pairs removed, on top of P1 LDS tables + P2 pointer SALU
# speedup vs baseline: 1.0019x; 1.0019x over previous
; #define PG8_STAGE(bufoff, gbase, voff) do { _Pragma("unroll") for (int _i = 0; _i < 2; ++_i) \
;         __builtin_amdgcn_global_load_lds((const unsigned*)((const char*)(gbase) + (voff)[_i]), (PG8_LAS unsigned*)(lds + (bufoff) + ldsw + _i * 8192), 16, 0, 0); } while (0)
; #define PG8_LDA(dst, b, h) do { _Pragma("unroll") for (int m = 0; m < 4; ++m) _Pragma("unroll") for (int k = 0; k < 2; ++k) dst[m][k] = *(const PG8_LAS bf16x8*)(lds + PG8_SA(b, h) + aoff + m * 2048 + k * 1024); } while (0)
; #define PG8_LDB(dst, b, h) do { _Pragma("unroll") for (int n = 0; n < 2; ++n) _Pragma("unroll") for (int k = 0; k < 2; ++k) dst[n][k] = *(const PG8_LAS bf16x8*)(lds + PG8_SB(b, h) + boff + n * 2048 + k * 1024); } while (0)
; #define PG8_MMA(ai, bj, At, Bt) do { __builtin_amdgcn_s_setprio(1); _Pragma("unroll") for (int m = 0; m < 4; ++m) _Pragma("unroll") for (int n = 0; n < 2; ++n) _Pragma("unroll") for (int k = 0; k < 2; ++k) \
;         acc[ai][bj][m][n] = __builtin_amdgcn_mfma_f32_16x16x32_bf16(Bt[n][k], At[m][k], acc[ai][bj][m][n], 0, 0, 0); __builtin_amdgcn_s_setprio(0); } while (0)
; #define PG8_WAIT_V(n) asm volatile("s_waitcnt vmcnt(" #n ")" ::: "memory")
; #define PG8_WAIT_L(n) asm volatile("s_waitcnt lgkmcnt(" #n ")" ::: "memory")
; #define PG8_BAR __builtin_amdgcn_s_barrier()
; #define PG8_SCHED __builtin_amdgcn_sched_barrier(0)
; template <class Epi, class Sched, bool ALIGN_EPI = false, bool SP2 = false>
; __device__ __forceinline__ void gemm_phase(PG8_LAS unsigned char* lds, const Gemm g, const Sched& S, const Epi& E) {
;     ...
;             const bool last = (t == nt - 2);
;             const char* a1 = cA + (size_t)(t + 1) * kstep;
;             const char* a2 = last ? nA : cA + (size_t)(t + 2) * kstep; const char* b2 = last ? nB : cB + (size_t)(t + 2) * kstep;
;             const char* a3 = a2 + kstep; const char* b3 = b2 + kstep;
;             if (last && has_next) S.a_ready(nxt);
;             if constexpr (SP2) {
;             PG8_LDB(B0, 0, 0); PG8_LDB(B1, 0, 1); PG8_SCHED; PG8_LDA(At, 0, 0); PG8_STAGE(PG8_SA(1, 1), a1 + hstep, voffA);
;             PG8_WAIT_V(8); PG8_WAIT_L(0); PG8_BAR; PG8_MMA(0, 0, At, B0); PG8_MMA(0, 1, At, B1); PG8_BAR; PG8_SCHED;
;             PG8_LDA(At, 0, 1); PG8_STAGE(PG8_SB(0, 0), b2, voffB); PG8_STAGE(PG8_SB(0, 1), b2 + hstep, voffB); PG8_STAGE(PG8_SA(0, 0), a2, voffA);
.LBB0_246:
	ds_read_b128 v[130:133], v201
	ds_read_b128 v[134:137], v201 offset:1024
	ds_read_b128 v[176:179], v201 offset:2048
	ds_read_b128 v[180:183], v201 offset:3072
	ds_read_b128 v[184:187], v202
	ds_read_b128 v[188:191], v202 offset:1024
	ds_read_b128 v[192:195], v202 offset:2048
	ds_read_b128 v[210:213], v202 offset:3072
	s_add_u32 s0, s28, 0xfffc0080
	s_addc_u32 s1, s29, -1
	s_cmp_eq_u32 s76, 12
	s_cselect_b32 s35, s21, s1
	s_cselect_b32 s34, vcc_lo, s0
	s_cselect_b32 s31, s19, s73
	s_cselect_b32 s30, vcc_hi, s72
	v_lshl_add_u64 v[196:197], s[28:29], 0, v[170:171]
	s_add_i32 m0, s41, 0xc000
	ds_read_b128 v[214:217], v198
	ds_read_b128 v[218:221], v198 offset:1024
	ds_read_b128 v[222:225], v198 offset:2048
	ds_read_b128 v[226:229], v198 offset:3072
	ds_read_b128 v[230:233], v198 offset:4096
	ds_read_b128 v[234:237], v198 offset:5120
	ds_read_b128 v[238:241], v198 offset:6144
	ds_read_b128 v[242:245], v198 offset:7168
	global_load_lds_dwordx4 v[196:197], off
	v_lshl_add_u64 v[196:197], s[28:29], 0, v[172:173]
	s_add_i32 m0, s41, 0xe000
	s_nop 0
	global_load_lds_dwordx4 v[196:197], off
	s_waitcnt vmcnt(8)
	s_waitcnt lgkmcnt(0)
	s_barrier
	s_setprio 1
	s_waitcnt lgkmcnt(0)
	v_mfma_f32_16x16x32_bf16 v[126:129], v[130:133], v[214:217], v[126:129]
	v_mfma_f32_16x16x32_bf16 v[122:125], v[176:179], v[214:217], v[122:125]
	v_mfma_f32_16x16x32_bf16 v[114:117], v[130:133], v[222:225], v[114:117]
	v_mfma_f32_16x16x32_bf16 v[106:109], v[176:179], v[222:225], v[106:109]
	v_mfma_f32_16x16x32_bf16 v[102:105], v[130:133], v[230:233], v[102:105]
	v_mfma_f32_16x16x32_bf16 v[94:97], v[176:179], v[230:233], v[94:97]
	v_mfma_f32_16x16x32_bf16 v[86:89], v[130:133], v[238:241], v[86:89]
	v_mfma_f32_16x16x32_bf16 v[78:81], v[176:179], v[238:241], v[78:81]
	v_mfma_f32_16x16x32_bf16 v[126:129], v[134:137], v[218:221], v[126:129]
	v_mfma_f32_16x16x32_bf16 v[122:125], v[180:183], v[218:221], v[122:125]
	v_mfma_f32_16x16x32_bf16 v[114:117], v[134:137], v[226:229], v[114:117]
	v_mfma_f32_16x16x32_bf16 v[106:109], v[180:183], v[226:229], v[106:109]
	v_mfma_f32_16x16x32_bf16 v[102:105], v[134:137], v[234:237], v[102:105]
	v_mfma_f32_16x16x32_bf16 v[94:97], v[180:183], v[234:237], v[94:97]
	v_mfma_f32_16x16x32_bf16 v[86:89], v[134:137], v[242:245], v[86:89]
	v_mfma_f32_16x16x32_bf16 v[78:81], v[180:183], v[242:245], v[78:81]
	v_mfma_f32_16x16x32_bf16 v[118:121], v[184:187], v[214:217], v[118:121]
	v_mfma_f32_16x16x32_bf16 v[110:113], v[192:195], v[214:217], v[110:113]
	v_mfma_f32_16x16x32_bf16 v[98:101], v[184:187], v[222:225], v[98:101]
	v_mfma_f32_16x16x32_bf16 v[90:93], v[192:195], v[222:225], v[90:93]
	v_mfma_f32_16x16x32_bf16 v[82:85], v[184:187], v[230:233], v[82:85]
	v_mfma_f32_16x16x32_bf16 v[74:77], v[192:195], v[230:233], v[74:77]
	v_mfma_f32_16x16x32_bf16 v[70:73], v[184:187], v[238:241], v[70:73]
	v_mfma_f32_16x16x32_bf16 v[66:69], v[192:195], v[238:241], v[66:69]
	v_mfma_f32_16x16x32_bf16 v[118:121], v[188:191], v[218:221], v[118:121]
	v_mfma_f32_16x16x32_bf16 v[110:113], v[210:213], v[218:221], v[110:113]
	v_mfma_f32_16x16x32_bf16 v[98:101], v[188:191], v[226:229], v[98:101]
	v_mfma_f32_16x16x32_bf16 v[90:93], v[210:213], v[226:229], v[90:93]
	v_mfma_f32_16x16x32_bf16 v[82:85], v[188:191], v[234:237], v[82:85]
	v_mfma_f32_16x16x32_bf16 v[74:77], v[210:213], v[234:237], v[74:77]
	v_mfma_f32_16x16x32_bf16 v[70:73], v[188:191], v[242:245], v[70:73]
	v_mfma_f32_16x16x32_bf16 v[66:69], v[210:213], v[242:245], v[66:69]
	s_setprio 0
	s_barrier
	s_add_i32 s0, s92, s38
	v_lshl_add_u64 v[196:197], s[30:31], 0, v[142:143]
	s_mov_b32 m0, s0
	ds_read_b128 v[214:217], v198 offset:16384
	ds_read_b128 v[218:221], v198 offset:17408
	ds_read_b128 v[222:225], v198 offset:18432
	ds_read_b128 v[226:229], v198 offset:19456
	ds_read_b128 v[230:233], v198 offset:20480
	ds_read_b128 v[234:237], v198 offset:21504
	ds_read_b128 v[238:241], v198 offset:22528
	ds_read_b128 v[242:245], v198 offset:23552
	global_load_lds_dwordx4 v[196:197], off
	s_add_i32 m0, s0, 0x2000
	s_add_u32 s0, s30, 0x40000
	v_lshl_add_u64 v[246:247], s[30:31], 0, v[138:139]
	s_addc_u32 s1, s31, 0
	s_add_i32 s77, s93, s38
	global_load_lds_dwordx4 v[246:247], off
	v_lshl_add_u64 v[248:249], s[0:1], 0, v[142:143]
	s_mov_b32 m0, s77
	v_lshl_add_u64 v[250:251], s[34:35], 0, v[140:141]
	global_load_lds_dwordx4 v[248:249], off
	v_lshl_add_u64 v[248:249], s[0:1], 0, v[138:139]
	s_add_i32 m0, s77, 0x2000
	s_nop 0
	global_load_lds_dwordx4 v[248:249], off
	v_lshl_add_u64 v[248:249], s[34:35], 0, v[144:145]
	s_mov_b32 m0, s41
	s_nop 0
	global_load_lds_dwordx4 v[248:249], off
	s_mov_b32 m0, s69
	s_nop 0
	global_load_lds_dwordx4 v[250:251], off
	s_waitcnt vmcnt(8)
	s_waitcnt lgkmcnt(0)
	s_barrier
; #define PG8_STAGE(bufoff, gbase, voff) do { _Pragma("unroll") for (int _i = 0; _i < 2; ++_i) \
;         __builtin_amdgcn_global_load_lds((const unsigned*)((const char*)(gbase) + (voff)[_i]), (PG8_LAS unsigned*)(lds + (bufoff) + ldsw + _i * 8192), 16, 0, 0); } while (0)
; #define PG8_LDA(dst, b, h) do { _Pragma("unroll") for (int m = 0; m < 4; ++m) _Pragma("unroll") for (int k = 0; k < 2; ++k) dst[m][k] = *(const PG8_LAS bf16x8*)(lds + PG8_SA(b, h) + aoff + m * 2048 + k * 1024); } while (0)
; #define PG8_LDB(dst, b, h) do { _Pragma("unroll") for (int n = 0; n < 2; ++n) _Pragma("unroll") for (int k = 0; k < 2; ++k) dst[n][k] = *(const PG8_LAS bf16x8*)(lds + PG8_SB(b, h) + boff + n * 2048 + k * 1024); } while (0)
; #define PG8_MMA(ai, bj, At, Bt) do { __builtin_amdgcn_s_setprio(1); _Pragma("unroll") for (int m = 0; m < 4; ++m) _Pragma("unroll") for (int n = 0; n < 2; ++n) _Pragma("unroll") for (int k = 0; k < 2; ++k) \
;         acc[ai][bj][m][n] = __builtin_amdgcn_mfma_f32_16x16x32_bf16(Bt[n][k], At[m][k], acc[ai][bj][m][n], 0, 0, 0); __builtin_amdgcn_s_setprio(0); } while (0)
; #define PG8_WAIT_V(n) asm volatile("s_waitcnt vmcnt(" #n ")" ::: "memory")
; #define PG8_WAIT_L(n) asm volatile("s_waitcnt lgkmcnt(" #n ")" ::: "memory")
; #define PG8_BAR __builtin_amdgcn_s_barrier()
; #define PG8_SCHED __builtin_amdgcn_sched_barrier(0)
; template <class Epi, class Sched, bool ALIGN_EPI = false, bool SP2 = false>
; __device__ __forceinline__ void gemm_phase(PG8_LAS unsigned char* lds, const Gemm g, const Sched& S, const Epi& E) {
;     ...
;             PG8_WAIT_V(8); PG8_WAIT_L(0); PG8_BAR; PG8_MMA(1, 0, At, B0); PG8_MMA(1, 1, At, B1); PG8_BAR; PG8_SCHED;
;             PG8_LDB(B0, 1, 0); PG8_LDB(B1, 1, 1); PG8_SCHED; PG8_LDA(At, 1, 0); PG8_STAGE(PG8_SA(0, 1), a2 + hstep, voffA);
;             PG8_WAIT_V(8); PG8_WAIT_L(0); PG8_BAR; PG8_MMA(0, 0, At, B0); PG8_MMA(0, 1, At, B1); PG8_BAR; PG8_SCHED;
	s_setprio 1
	s_waitcnt lgkmcnt(0)
	v_mfma_f32_16x16x32_bf16 v[62:65], v[130:133], v[214:217], v[62:65]
	v_mfma_f32_16x16x32_bf16 v[58:61], v[176:179], v[214:217], v[58:61]
	v_mfma_f32_16x16x32_bf16 v[54:57], v[130:133], v[222:225], v[54:57]
	v_mfma_f32_16x16x32_bf16 v[46:49], v[176:179], v[222:225], v[46:49]
	v_mfma_f32_16x16x32_bf16 v[38:41], v[130:133], v[230:233], v[38:41]
	v_mfma_f32_16x16x32_bf16 v[30:33], v[176:179], v[230:233], v[30:33]
	v_mfma_f32_16x16x32_bf16 v[22:25], v[130:133], v[238:241], v[22:25]
	v_mfma_f32_16x16x32_bf16 v[14:17], v[176:179], v[238:241], v[14:17]
	v_mfma_f32_16x16x32_bf16 v[62:65], v[134:137], v[218:221], v[62:65]
	v_mfma_f32_16x16x32_bf16 v[58:61], v[180:183], v[218:221], v[58:61]
	v_mfma_f32_16x16x32_bf16 v[54:57], v[134:137], v[226:229], v[54:57]
	v_mfma_f32_16x16x32_bf16 v[46:49], v[180:183], v[226:229], v[46:49]
	v_mfma_f32_16x16x32_bf16 v[38:41], v[134:137], v[234:237], v[38:41]
	v_mfma_f32_16x16x32_bf16 v[30:33], v[180:183], v[234:237], v[30:33]
	v_mfma_f32_16x16x32_bf16 v[22:25], v[134:137], v[242:245], v[22:25]
	v_mfma_f32_16x16x32_bf16 v[14:17], v[180:183], v[242:245], v[14:17]
	v_mfma_f32_16x16x32_bf16 v[50:53], v[184:187], v[214:217], v[50:53]
	v_mfma_f32_16x16x32_bf16 v[42:45], v[192:195], v[214:217], v[42:45]
	v_mfma_f32_16x16x32_bf16 v[34:37], v[184:187], v[222:225], v[34:37]
	v_mfma_f32_16x16x32_bf16 v[26:29], v[192:195], v[222:225], v[26:29]
	v_mfma_f32_16x16x32_bf16 v[18:21], v[184:187], v[230:233], v[18:21]
	v_mfma_f32_16x16x32_bf16 v[10:13], v[192:195], v[230:233], v[10:13]
	v_mfma_f32_16x16x32_bf16 v[6:9], v[184:187], v[238:241], v[6:9]
	v_mfma_f32_16x16x32_bf16 v[2:5], v[192:195], v[238:241], v[2:5]
	v_mfma_f32_16x16x32_bf16 v[50:53], v[188:191], v[218:221], v[50:53]
	v_mfma_f32_16x16x32_bf16 v[42:45], v[210:213], v[218:221], v[42:45]
	v_mfma_f32_16x16x32_bf16 v[34:37], v[188:191], v[226:229], v[34:37]
	v_mfma_f32_16x16x32_bf16 v[26:29], v[210:213], v[226:229], v[26:29]
	v_mfma_f32_16x16x32_bf16 v[18:21], v[188:191], v[234:237], v[18:21]
	v_mfma_f32_16x16x32_bf16 v[10:13], v[210:213], v[234:237], v[10:13]
	v_mfma_f32_16x16x32_bf16 v[6:9], v[188:191], v[242:245], v[6:9]
	v_mfma_f32_16x16x32_bf16 v[2:5], v[210:213], v[242:245], v[2:5]
	s_setprio 0
	s_barrier
	ds_read_b128 v[130:133], v203
	ds_read_b128 v[134:137], v203 offset:1024
	ds_read_b128 v[176:179], v203 offset:2048
	ds_read_b128 v[180:183], v203 offset:3072
	ds_read_b128 v[184:187], v204
	ds_read_b128 v[188:191], v204 offset:1024
	ds_read_b128 v[192:195], v204 offset:2048
	ds_read_b128 v[210:213], v204 offset:3072
	s_add_u32 s0, s34, 0x40000
	s_addc_u32 s1, s35, 0
	s_mov_b32 m0, s82
	v_lshl_add_u64 v[252:253], s[0:1], 0, v[144:145]
	ds_read_b128 v[214:217], v198 offset:32768
	ds_read_b128 v[218:221], v198 offset:33792
	ds_read_b128 v[222:225], v198 offset:34816
	ds_read_b128 v[226:229], v198 offset:35840
	ds_read_b128 v[230:233], v198 offset:36864
	ds_read_b128 v[234:237], v198 offset:37888
	ds_read_b128 v[238:241], v198 offset:38912
	ds_read_b128 v[242:245], v198 offset:39936
	global_load_lds_dwordx4 v[252:253], off
	v_lshl_add_u64 v[252:253], s[0:1], 0, v[140:141]
	s_mov_b32 m0, s83
	s_nop 0
	global_load_lds_dwordx4 v[252:253], off
	s_waitcnt vmcnt(8)
	s_waitcnt lgkmcnt(0)
	s_barrier
	s_setprio 1
	s_waitcnt lgkmcnt(0)
	v_mfma_f32_16x16x32_bf16 v[126:129], v[130:133], v[214:217], v[126:129]
	v_mfma_f32_16x16x32_bf16 v[122:125], v[176:179], v[214:217], v[122:125]
	v_mfma_f32_16x16x32_bf16 v[114:117], v[130:133], v[222:225], v[114:117]
	v_mfma_f32_16x16x32_bf16 v[106:109], v[176:179], v[222:225], v[106:109]
	v_mfma_f32_16x16x32_bf16 v[102:105], v[130:133], v[230:233], v[102:105]
	v_mfma_f32_16x16x32_bf16 v[94:97], v[176:179], v[230:233], v[94:97]
	v_mfma_f32_16x16x32_bf16 v[86:89], v[130:133], v[238:241], v[86:89]
	v_mfma_f32_16x16x32_bf16 v[78:81], v[176:179], v[238:241], v[78:81]
	v_mfma_f32_16x16x32_bf16 v[126:129], v[134:137], v[218:221], v[126:129]
	v_mfma_f32_16x16x32_bf16 v[122:125], v[180:183], v[218:221], v[122:125]
	v_mfma_f32_16x16x32_bf16 v[114:117], v[134:137], v[226:229], v[114:117]
	v_mfma_f32_16x16x32_bf16 v[106:109], v[180:183], v[226:229], v[106:109]
	v_mfma_f32_16x16x32_bf16 v[102:105], v[134:137], v[234:237], v[102:105]
	v_mfma_f32_16x16x32_bf16 v[94:97], v[180:183], v[234:237], v[94:97]
	v_mfma_f32_16x16x32_bf16 v[86:89], v[134:137], v[242:245], v[86:89]
	v_mfma_f32_16x16x32_bf16 v[78:81], v[180:183], v[242:245], v[78:81]
	v_mfma_f32_16x16x32_bf16 v[118:121], v[184:187], v[214:217], v[118:121]
	v_mfma_f32_16x16x32_bf16 v[110:113], v[192:195], v[214:217], v[110:113]
	v_mfma_f32_16x16x32_bf16 v[98:101], v[184:187], v[222:225], v[98:101]
	v_mfma_f32_16x16x32_bf16 v[90:93], v[192:195], v[222:225], v[90:93]
	v_mfma_f32_16x16x32_bf16 v[82:85], v[184:187], v[230:233], v[82:85]
	v_mfma_f32_16x16x32_bf16 v[74:77], v[192:195], v[230:233], v[74:77]
	v_mfma_f32_16x16x32_bf16 v[70:73], v[184:187], v[238:241], v[70:73]
	v_mfma_f32_16x16x32_bf16 v[66:69], v[192:195], v[238:241], v[66:69]
	v_mfma_f32_16x16x32_bf16 v[118:121], v[188:191], v[218:221], v[118:121]
	v_mfma_f32_16x16x32_bf16 v[110:113], v[210:213], v[218:221], v[110:113]
	v_mfma_f32_16x16x32_bf16 v[98:101], v[188:191], v[226:229], v[98:101]
	v_mfma_f32_16x16x32_bf16 v[90:93], v[210:213], v[226:229], v[90:93]
	v_mfma_f32_16x16x32_bf16 v[82:85], v[188:191], v[234:237], v[82:85]
	v_mfma_f32_16x16x32_bf16 v[74:77], v[210:213], v[234:237], v[74:77]
	v_mfma_f32_16x16x32_bf16 v[70:73], v[188:191], v[242:245], v[70:73]
	v_mfma_f32_16x16x32_bf16 v[66:69], v[210:213], v[242:245], v[66:69]
	s_setprio 0
	s_barrier
; #define PG8_STAGE(bufoff, gbase, voff) do { _Pragma("unroll") for (int _i = 0; _i < 2; ++_i) \
;         __builtin_amdgcn_global_load_lds((const unsigned*)((const char*)(gbase) + (voff)[_i]), (PG8_LAS unsigned*)(lds + (bufoff) + ldsw + _i * 8192), 16, 0, 0); } while (0)
; #define PG8_LDA(dst, b, h) do { _Pragma("unroll") for (int m = 0; m < 4; ++m) _Pragma("unroll") for (int k = 0; k < 2; ++k) dst[m][k] = *(const PG8_LAS bf16x8*)(lds + PG8_SA(b, h) + aoff + m * 2048 + k * 1024); } while (0)
; #define PG8_MMA(ai, bj, At, Bt) do { __builtin_amdgcn_s_setprio(1); _Pragma("unroll") for (int m = 0; m < 4; ++m) _Pragma("unroll") for (int n = 0; n < 2; ++n) _Pragma("unroll") for (int k = 0; k < 2; ++k) \
;         acc[ai][bj][m][n] = __builtin_amdgcn_mfma_f32_16x16x32_bf16(Bt[n][k], At[m][k], acc[ai][bj][m][n], 0, 0, 0); __builtin_amdgcn_s_setprio(0); } while (0)
; #define PG8_WAIT_V(n) asm volatile("s_waitcnt vmcnt(" #n ")" ::: "memory")
; #define PG8_WAIT_L(n) asm volatile("s_waitcnt lgkmcnt(" #n ")" ::: "memory")
; #define PG8_BAR __builtin_amdgcn_s_barrier()
; #define PG8_SCHED __builtin_amdgcn_sched_barrier(0)
; template <class Epi, class Sched, bool ALIGN_EPI = false, bool SP2 = false>
; __device__ __forceinline__ void gemm_phase(PG8_LAS unsigned char* lds, const Gemm g, const Sched& S, const Epi& E) {
;     ...
;             PG8_LDA(At, 1, 1); PG8_STAGE(PG8_SB(1, 0), b3, voffB); PG8_STAGE(PG8_SB(1, 1), b3 + hstep, voffB); PG8_STAGE(PG8_SA(1, 0), a3, voffA);
;             PG8_WAIT_V(8); PG8_WAIT_L(0); PG8_BAR; PG8_MMA(1, 0, At, B0); PG8_MMA(1, 1, At, B1); PG8_BAR; PG8_SCHED;
;     ...
;         if constexpr (ALIGN_EPI) { if (wr == 0) PG8_BAR; }
	s_add_i32 s0, s94, s38
	v_lshl_add_u64 v[196:197], v[196:197], 0, s[6:7]
	s_mov_b32 m0, s0
	ds_read_b128 v[214:217], v198 offset:49152
	ds_read_b128 v[218:221], v198 offset:50176
	ds_read_b128 v[222:225], v198 offset:51200
	ds_read_b128 v[226:229], v198 offset:52224
	ds_read_b128 v[230:233], v198 offset:53248
	ds_read_b128 v[234:237], v198 offset:54272
	ds_read_b128 v[238:241], v198 offset:55296
	ds_read_b128 v[242:245], v198 offset:56320
	global_load_lds_dwordx4 v[196:197], off
	s_add_i32 m0, s0, 0x2000
	s_add_u32 s0, s30, 0x40080
	v_lshl_add_u64 v[196:197], v[246:247], 0, s[6:7]
	s_addc_u32 s1, s31, 0
	s_add_i32 s30, s95, s38
	global_load_lds_dwordx4 v[196:197], off
	v_lshl_add_u64 v[196:197], s[0:1], 0, v[142:143]
	s_mov_b32 m0, s30
	s_nop 0
	global_load_lds_dwordx4 v[196:197], off
	v_lshl_add_u64 v[196:197], s[0:1], 0, v[138:139]
	s_add_i32 m0, s30, 0x2000
	s_nop 0
	global_load_lds_dwordx4 v[196:197], off
	v_lshl_add_u64 v[196:197], v[248:249], 0, s[6:7]
	s_mov_b32 m0, s85
	s_nop 0
	global_load_lds_dwordx4 v[196:197], off
	v_lshl_add_u64 v[196:197], v[250:251], 0, s[6:7]
	s_mov_b32 m0, s89
	s_nop 0
	global_load_lds_dwordx4 v[196:197], off
	s_waitcnt vmcnt(8)
	s_waitcnt lgkmcnt(0)
	s_barrier
	s_setprio 1
	s_waitcnt lgkmcnt(0)
	v_mfma_f32_16x16x32_bf16 v[62:65], v[130:133], v[214:217], v[62:65]
	v_mfma_f32_16x16x32_bf16 v[58:61], v[176:179], v[214:217], v[58:61]
	v_mfma_f32_16x16x32_bf16 v[54:57], v[130:133], v[222:225], v[54:57]
	v_mfma_f32_16x16x32_bf16 v[46:49], v[176:179], v[222:225], v[46:49]
	v_mfma_f32_16x16x32_bf16 v[38:41], v[130:133], v[230:233], v[38:41]
	v_mfma_f32_16x16x32_bf16 v[30:33], v[176:179], v[230:233], v[30:33]
	v_mfma_f32_16x16x32_bf16 v[22:25], v[130:133], v[238:241], v[22:25]
	v_mfma_f32_16x16x32_bf16 v[14:17], v[176:179], v[238:241], v[14:17]
	v_mfma_f32_16x16x32_bf16 v[62:65], v[134:137], v[218:221], v[62:65]
	v_mfma_f32_16x16x32_bf16 v[58:61], v[180:183], v[218:221], v[58:61]
	v_mfma_f32_16x16x32_bf16 v[54:57], v[134:137], v[226:229], v[54:57]
	v_mfma_f32_16x16x32_bf16 v[46:49], v[180:183], v[226:229], v[46:49]
	v_mfma_f32_16x16x32_bf16 v[38:41], v[134:137], v[234:237], v[38:41]
	v_mfma_f32_16x16x32_bf16 v[30:33], v[180:183], v[234:237], v[30:33]
	v_mfma_f32_16x16x32_bf16 v[22:25], v[134:137], v[242:245], v[22:25]
	v_mfma_f32_16x16x32_bf16 v[14:17], v[180:183], v[242:245], v[14:17]
	v_mfma_f32_16x16x32_bf16 v[50:53], v[184:187], v[214:217], v[50:53]
	v_mfma_f32_16x16x32_bf16 v[42:45], v[192:195], v[214:217], v[42:45]
	v_mfma_f32_16x16x32_bf16 v[34:37], v[184:187], v[222:225], v[34:37]
	v_mfma_f32_16x16x32_bf16 v[26:29], v[192:195], v[222:225], v[26:29]
	v_mfma_f32_16x16x32_bf16 v[18:21], v[184:187], v[230:233], v[18:21]
	v_mfma_f32_16x16x32_bf16 v[10:13], v[192:195], v[230:233], v[10:13]
	v_mfma_f32_16x16x32_bf16 v[6:9], v[184:187], v[238:241], v[6:9]
	v_mfma_f32_16x16x32_bf16 v[2:5], v[192:195], v[238:241], v[2:5]
	v_mfma_f32_16x16x32_bf16 v[50:53], v[188:191], v[218:221], v[50:53]
	v_mfma_f32_16x16x32_bf16 v[42:45], v[210:213], v[218:221], v[42:45]
	v_mfma_f32_16x16x32_bf16 v[34:37], v[188:191], v[226:229], v[34:37]
	v_mfma_f32_16x16x32_bf16 v[26:29], v[210:213], v[226:229], v[26:29]
	v_mfma_f32_16x16x32_bf16 v[18:21], v[188:191], v[234:237], v[18:21]
	v_mfma_f32_16x16x32_bf16 v[10:13], v[210:213], v[234:237], v[10:13]
	v_mfma_f32_16x16x32_bf16 v[6:9], v[188:191], v[242:245], v[6:9]
	v_mfma_f32_16x16x32_bf16 v[2:5], v[210:213], v[242:245], v[2:5]
	s_setprio 0
	s_barrier
	s_add_i32 s76, s76, 2
	s_add_u32 s28, s28, 0x100
	s_addc_u32 s29, s29, 0
	s_add_u32 s72, s72, 0x100
	s_addc_u32 s73, s73, 0
	s_cmp_gt_u32 s76, 13
	s_cbranch_scc0 .LBB0_246
	s_and_b64 vcc, exec, s[8:9]
	s_cbranch_vccz .LBB0_249
	s_barrier

; #define PG8_STAGE(bufoff, gbase, voff) do { _Pragma("unroll") for (int _i = 0; _i < 2; ++_i) \
;         __builtin_amdgcn_global_load_lds((const unsigned*)((const char*)(gbase) + (voff)[_i]), (PG8_LAS unsigned*)(lds + (bufoff) + ldsw + _i * 8192), 16, 0, 0); } while (0)
; #define PG8_LDA(dst, b, h) do { _Pragma("unroll") for (int m = 0; m < 4; ++m) _Pragma("unroll") for (int k = 0; k < 2; ++k) dst[m][k] = *(const PG8_LAS bf16x8*)(lds + PG8_SA(b, h) + aoff + m * 2048 + k * 1024); } while (0)
; #define PG8_LDB(dst, b, h) do { _Pragma("unroll") for (int n = 0; n < 2; ++n) _Pragma("unroll") for (int k = 0; k < 2; ++k) dst[n][k] = *(const PG8_LAS bf16x8*)(lds + PG8_SB(b, h) + boff + n * 2048 + k * 1024); } while (0)
; #define PG8_MMA(ai, bj, At, Bt) do { __builtin_amdgcn_s_setprio(1); _Pragma("unroll") for (int m = 0; m < 4; ++m) _Pragma("unroll") for (int n = 0; n < 2; ++n) _Pragma("unroll") for (int k = 0; k < 2; ++k) \
;         acc[ai][bj][m][n] = __builtin_amdgcn_mfma_f32_16x16x32_bf16(Bt[n][k], At[m][k], acc[ai][bj][m][n], 0, 0, 0); __builtin_amdgcn_s_setprio(0); } while (0)
; #define PG8_WAIT_V(n) asm volatile("s_waitcnt vmcnt(" #n ")" ::: "memory")
; #define PG8_WAIT_L(n) asm volatile("s_waitcnt lgkmcnt(" #n ")" ::: "memory")
; #define PG8_BAR __builtin_amdgcn_s_barrier()
; #define PG8_SCHED __builtin_amdgcn_sched_barrier(0)
; template <class Epi, class Sched, bool ALIGN_EPI = false, bool SP2 = false>
; __device__ __forceinline__ void gemm_phase(PG8_LAS unsigned char* lds, const Gemm g, const Sched& S, const Epi& E) {
;     ...
;             const bool last = (t == nt - 2);
;             const char* a1 = cA + (size_t)(t + 1) * kstep;
;             const char* a2 = last ? nA : cA + (size_t)(t + 2) * kstep; const char* b2 = last ? nB : cB + (size_t)(t + 2) * kstep;
;             const char* a3 = a2 + kstep; const char* b3 = b2 + kstep;
;             if (last && has_next) S.a_ready(nxt);
;             if constexpr (SP2) {
;             PG8_LDB(B0, 0, 0); PG8_LDB(B1, 0, 1); PG8_SCHED; PG8_LDA(At, 0, 0); PG8_STAGE(PG8_SA(1, 1), a1 + hstep, voffA);
;             PG8_WAIT_V(8); PG8_WAIT_L(0); PG8_BAR; PG8_MMA(0, 0, At, B0); PG8_MMA(0, 1, At, B1); PG8_BAR; PG8_SCHED;
;             PG8_LDA(At, 0, 1); PG8_STAGE(PG8_SB(0, 0), b2, voffB); PG8_STAGE(PG8_SB(0, 1), b2 + hstep, voffB); PG8_STAGE(PG8_SA(0, 0), a2, voffA);
.LBB0_1230:
	ds_read_b128 v[144:147], v166
	ds_read_b128 v[148:151], v166 offset:1024
	ds_read_b128 v[152:155], v166 offset:2048
	ds_read_b128 v[172:175], v166 offset:3072
	ds_read_b128 v[176:179], v167
	ds_read_b128 v[180:183], v167 offset:1024
	ds_read_b128 v[184:187], v167 offset:2048
	ds_read_b128 v[188:191], v167 offset:3072
	s_add_u32 s0, s30, 0xfffc0080
	s_addc_u32 s1, s31, -1
	s_cmp_eq_u32 s76, 12
	s_cselect_b32 s37, s21, s1
	s_cselect_b32 s36, s29, s0
	s_cselect_b32 s35, s19, s73
	s_cselect_b32 s34, s84, s72
	v_lshl_add_u64 v[226:227], s[30:31], 0, v[138:139]
	s_add_i32 m0, s40, 0xc000
	ds_read_b128 v[192:195], v168
	ds_read_b128 v[196:199], v168 offset:1024
	ds_read_b128 v[200:203], v168 offset:2048
	ds_read_b128 v[204:207], v168 offset:3072
	ds_read_b128 v[210:213], v168 offset:4096
	ds_read_b128 v[214:217], v168 offset:5120
	ds_read_b128 v[218:221], v168 offset:6144
	ds_read_b128 v[222:225], v168 offset:7168
	global_load_lds_dwordx4 v[226:227], off
	v_lshl_add_u64 v[226:227], s[30:31], 0, v[140:141]
	s_add_i32 m0, s40, 0xe000
	s_nop 0
	global_load_lds_dwordx4 v[226:227], off
	s_waitcnt vmcnt(8)
	s_waitcnt lgkmcnt(0)
	s_barrier
	s_setprio 1
	s_waitcnt lgkmcnt(0)
	v_mfma_f32_16x16x32_bf16 v[126:129], v[144:147], v[192:195], v[126:129]
	v_mfma_f32_16x16x32_bf16 v[122:125], v[152:155], v[192:195], v[122:125]
	v_mfma_f32_16x16x32_bf16 v[110:113], v[144:147], v[200:203], v[110:113]
	v_mfma_f32_16x16x32_bf16 v[106:109], v[152:155], v[200:203], v[106:109]
	v_mfma_f32_16x16x32_bf16 v[94:97], v[144:147], v[210:213], v[94:97]
	v_mfma_f32_16x16x32_bf16 v[90:93], v[152:155], v[210:213], v[90:93]
	v_mfma_f32_16x16x32_bf16 v[78:81], v[144:147], v[218:221], v[78:81]
	v_mfma_f32_16x16x32_bf16 v[74:77], v[152:155], v[218:221], v[74:77]
	v_mfma_f32_16x16x32_bf16 v[126:129], v[148:151], v[196:199], v[126:129]
	v_mfma_f32_16x16x32_bf16 v[122:125], v[172:175], v[196:199], v[122:125]
	v_mfma_f32_16x16x32_bf16 v[110:113], v[148:151], v[204:207], v[110:113]
	v_mfma_f32_16x16x32_bf16 v[106:109], v[172:175], v[204:207], v[106:109]
	v_mfma_f32_16x16x32_bf16 v[94:97], v[148:151], v[214:217], v[94:97]
	v_mfma_f32_16x16x32_bf16 v[90:93], v[172:175], v[214:217], v[90:93]
	v_mfma_f32_16x16x32_bf16 v[78:81], v[148:151], v[222:225], v[78:81]
	v_mfma_f32_16x16x32_bf16 v[74:77], v[172:175], v[222:225], v[74:77]
	v_mfma_f32_16x16x32_bf16 v[118:121], v[176:179], v[192:195], v[118:121]
	v_mfma_f32_16x16x32_bf16 v[114:117], v[184:187], v[192:195], v[114:117]
	v_mfma_f32_16x16x32_bf16 v[102:105], v[176:179], v[200:203], v[102:105]
	v_mfma_f32_16x16x32_bf16 v[98:101], v[184:187], v[200:203], v[98:101]
	v_mfma_f32_16x16x32_bf16 v[86:89], v[176:179], v[210:213], v[86:89]
	v_mfma_f32_16x16x32_bf16 v[82:85], v[184:187], v[210:213], v[82:85]
	v_mfma_f32_16x16x32_bf16 v[70:73], v[176:179], v[218:221], v[70:73]
	v_mfma_f32_16x16x32_bf16 v[66:69], v[184:187], v[218:221], v[66:69]
	v_mfma_f32_16x16x32_bf16 v[118:121], v[180:183], v[196:199], v[118:121]
	v_mfma_f32_16x16x32_bf16 v[114:117], v[188:191], v[196:199], v[114:117]
	v_mfma_f32_16x16x32_bf16 v[102:105], v[180:183], v[204:207], v[102:105]
	v_mfma_f32_16x16x32_bf16 v[98:101], v[188:191], v[204:207], v[98:101]
	v_mfma_f32_16x16x32_bf16 v[86:89], v[180:183], v[214:217], v[86:89]
	v_mfma_f32_16x16x32_bf16 v[82:85], v[188:191], v[214:217], v[82:85]
	v_mfma_f32_16x16x32_bf16 v[70:73], v[180:183], v[222:225], v[70:73]
	v_mfma_f32_16x16x32_bf16 v[66:69], v[188:191], v[222:225], v[66:69]
	s_setprio 0
	s_barrier
	s_add_i32 s0, s58, s39
	v_lshl_add_u64 v[226:227], s[34:35], 0, v[132:133]
	s_mov_b32 m0, s0
	ds_read_b128 v[192:195], v168 offset:16384
	ds_read_b128 v[196:199], v168 offset:17408
	ds_read_b128 v[200:203], v168 offset:18432
	ds_read_b128 v[204:207], v168 offset:19456
	ds_read_b128 v[210:213], v168 offset:20480
	ds_read_b128 v[214:217], v168 offset:21504
	ds_read_b128 v[218:221], v168 offset:22528
	ds_read_b128 v[222:225], v168 offset:23552
	global_load_lds_dwordx4 v[226:227], off
	s_add_i32 m0, s0, 0x2000
	s_add_u32 s0, s34, 0x40000
	v_lshl_add_u64 v[228:229], s[34:35], 0, v[136:137]
	s_addc_u32 s1, s35, 0
	s_add_i32 s77, s59, s39
	global_load_lds_dwordx4 v[228:229], off
	v_lshl_add_u64 v[230:231], s[0:1], 0, v[132:133]
	s_mov_b32 m0, s77
	v_lshl_add_u64 v[232:233], s[36:37], 0, v[134:135]
	global_load_lds_dwordx4 v[230:231], off
	v_lshl_add_u64 v[230:231], s[0:1], 0, v[136:137]
	s_add_i32 m0, s77, 0x2000
	s_nop 0
	global_load_lds_dwordx4 v[230:231], off
	v_lshl_add_u64 v[230:231], s[36:37], 0, v[130:131]
	s_mov_b32 m0, s40
	s_nop 0
	global_load_lds_dwordx4 v[230:231], off
	s_mov_b32 m0, s41
	s_nop 0
	global_load_lds_dwordx4 v[232:233], off
	s_waitcnt vmcnt(8)
	s_waitcnt lgkmcnt(0)
	s_barrier
; #define PG8_STAGE(bufoff, gbase, voff) do { _Pragma("unroll") for (int _i = 0; _i < 2; ++_i) \
;         __builtin_amdgcn_global_load_lds((const unsigned*)((const char*)(gbase) + (voff)[_i]), (PG8_LAS unsigned*)(lds + (bufoff) + ldsw + _i * 8192), 16, 0, 0); } while (0)
; #define PG8_LDA(dst, b, h) do { _Pragma("unroll") for (int m = 0; m < 4; ++m) _Pragma("unroll") for (int k = 0; k < 2; ++k) dst[m][k] = *(const PG8_LAS bf16x8*)(lds + PG8_SA(b, h) + aoff + m * 2048 + k * 1024); } while (0)
; #define PG8_LDB(dst, b, h) do { _Pragma("unroll") for (int n = 0; n < 2; ++n) _Pragma("unroll") for (int k = 0; k < 2; ++k) dst[n][k] = *(const PG8_LAS bf16x8*)(lds + PG8_SB(b, h) + boff + n * 2048 + k * 1024); } while (0)
; #define PG8_MMA(ai, bj, At, Bt) do { __builtin_amdgcn_s_setprio(1); _Pragma("unroll") for (int m = 0; m < 4; ++m) _Pragma("unroll") for (int n = 0; n < 2; ++n) _Pragma("unroll") for (int k = 0; k < 2; ++k) \
;         acc[ai][bj][m][n] = __builtin_amdgcn_mfma_f32_16x16x32_bf16(Bt[n][k], At[m][k], acc[ai][bj][m][n], 0, 0, 0); __builtin_amdgcn_s_setprio(0); } while (0)
; #define PG8_WAIT_V(n) asm volatile("s_waitcnt vmcnt(" #n ")" ::: "memory")
; #define PG8_WAIT_L(n) asm volatile("s_waitcnt lgkmcnt(" #n ")" ::: "memory")
; #define PG8_BAR __builtin_amdgcn_s_barrier()
; #define PG8_SCHED __builtin_amdgcn_sched_barrier(0)
; template <class Epi, class Sched, bool ALIGN_EPI = false, bool SP2 = false>
; __device__ __forceinline__ void gemm_phase(PG8_LAS unsigned char* lds, const Gemm g, const Sched& S, const Epi& E) {
;     ...
;             PG8_WAIT_V(8); PG8_WAIT_L(0); PG8_BAR; PG8_MMA(1, 0, At, B0); PG8_MMA(1, 1, At, B1); PG8_BAR; PG8_SCHED;
;             PG8_LDB(B0, 1, 0); PG8_LDB(B1, 1, 1); PG8_SCHED; PG8_LDA(At, 1, 0); PG8_STAGE(PG8_SA(0, 1), a2 + hstep, voffA);
;             PG8_WAIT_V(8); PG8_WAIT_L(0); PG8_BAR; PG8_MMA(0, 0, At, B0); PG8_MMA(0, 1, At, B1); PG8_BAR; PG8_SCHED;
	s_setprio 1
	s_waitcnt lgkmcnt(0)
	v_mfma_f32_16x16x32_bf16 v[62:65], v[144:147], v[192:195], v[62:65]
	v_mfma_f32_16x16x32_bf16 v[58:61], v[152:155], v[192:195], v[58:61]
	v_mfma_f32_16x16x32_bf16 v[46:49], v[144:147], v[200:203], v[46:49]
	v_mfma_f32_16x16x32_bf16 v[42:45], v[152:155], v[200:203], v[42:45]
	v_mfma_f32_16x16x32_bf16 v[30:33], v[144:147], v[210:213], v[30:33]
	v_mfma_f32_16x16x32_bf16 v[26:29], v[152:155], v[210:213], v[26:29]
	v_mfma_f32_16x16x32_bf16 v[14:17], v[144:147], v[218:221], v[14:17]
	v_mfma_f32_16x16x32_bf16 v[10:13], v[152:155], v[218:221], v[10:13]
	v_mfma_f32_16x16x32_bf16 v[62:65], v[148:151], v[196:199], v[62:65]
	v_mfma_f32_16x16x32_bf16 v[58:61], v[172:175], v[196:199], v[58:61]
	v_mfma_f32_16x16x32_bf16 v[46:49], v[148:151], v[204:207], v[46:49]
	v_mfma_f32_16x16x32_bf16 v[42:45], v[172:175], v[204:207], v[42:45]
	v_mfma_f32_16x16x32_bf16 v[30:33], v[148:151], v[214:217], v[30:33]
	v_mfma_f32_16x16x32_bf16 v[26:29], v[172:175], v[214:217], v[26:29]
	v_mfma_f32_16x16x32_bf16 v[14:17], v[148:151], v[222:225], v[14:17]
	v_mfma_f32_16x16x32_bf16 v[10:13], v[172:175], v[222:225], v[10:13]
	v_mfma_f32_16x16x32_bf16 v[54:57], v[176:179], v[192:195], v[54:57]
	v_mfma_f32_16x16x32_bf16 v[50:53], v[184:187], v[192:195], v[50:53]
	v_mfma_f32_16x16x32_bf16 v[38:41], v[176:179], v[200:203], v[38:41]
	v_mfma_f32_16x16x32_bf16 v[34:37], v[184:187], v[200:203], v[34:37]
	v_mfma_f32_16x16x32_bf16 v[22:25], v[176:179], v[210:213], v[22:25]
	v_mfma_f32_16x16x32_bf16 v[18:21], v[184:187], v[210:213], v[18:21]
	v_mfma_f32_16x16x32_bf16 v[6:9], v[176:179], v[218:221], v[6:9]
	v_mfma_f32_16x16x32_bf16 v[2:5], v[184:187], v[218:221], v[2:5]
	v_mfma_f32_16x16x32_bf16 v[54:57], v[180:183], v[196:199], v[54:57]
	v_mfma_f32_16x16x32_bf16 v[50:53], v[188:191], v[196:199], v[50:53]
	v_mfma_f32_16x16x32_bf16 v[38:41], v[180:183], v[204:207], v[38:41]
	v_mfma_f32_16x16x32_bf16 v[34:37], v[188:191], v[204:207], v[34:37]
	v_mfma_f32_16x16x32_bf16 v[22:25], v[180:183], v[214:217], v[22:25]
	v_mfma_f32_16x16x32_bf16 v[18:21], v[188:191], v[214:217], v[18:21]
	v_mfma_f32_16x16x32_bf16 v[6:9], v[180:183], v[222:225], v[6:9]
	v_mfma_f32_16x16x32_bf16 v[2:5], v[188:191], v[222:225], v[2:5]
	s_setprio 0
	s_barrier
	ds_read_b128 v[144:147], v170
	ds_read_b128 v[148:151], v170 offset:1024
	ds_read_b128 v[152:155], v170 offset:2048
	ds_read_b128 v[172:175], v170 offset:3072
	ds_read_b128 v[176:179], v171
	ds_read_b128 v[180:183], v171 offset:1024
	ds_read_b128 v[184:187], v171 offset:2048
	ds_read_b128 v[188:191], v171 offset:3072
	s_add_u32 s0, s36, 0x40000
	s_addc_u32 s1, s37, 0
	s_mov_b32 m0, s43
	v_lshl_add_u64 v[234:235], s[0:1], 0, v[130:131]
	ds_read_b128 v[192:195], v168 offset:32768
	ds_read_b128 v[196:199], v168 offset:33792
	ds_read_b128 v[200:203], v168 offset:34816
	ds_read_b128 v[204:207], v168 offset:35840
	ds_read_b128 v[210:213], v168 offset:36864
	ds_read_b128 v[214:217], v168 offset:37888
	ds_read_b128 v[218:221], v168 offset:38912
	ds_read_b128 v[222:225], v168 offset:39936
	global_load_lds_dwordx4 v[234:235], off
	v_lshl_add_u64 v[234:235], s[0:1], 0, v[134:135]
	s_mov_b32 m0, s52
	s_nop 0
	global_load_lds_dwordx4 v[234:235], off
	s_waitcnt vmcnt(8)
	s_waitcnt lgkmcnt(0)
	s_barrier
	s_setprio 1
	s_waitcnt lgkmcnt(0)
	v_mfma_f32_16x16x32_bf16 v[126:129], v[144:147], v[192:195], v[126:129]
	v_mfma_f32_16x16x32_bf16 v[122:125], v[152:155], v[192:195], v[122:125]
	v_mfma_f32_16x16x32_bf16 v[110:113], v[144:147], v[200:203], v[110:113]
	v_mfma_f32_16x16x32_bf16 v[106:109], v[152:155], v[200:203], v[106:109]
	v_mfma_f32_16x16x32_bf16 v[94:97], v[144:147], v[210:213], v[94:97]
	v_mfma_f32_16x16x32_bf16 v[90:93], v[152:155], v[210:213], v[90:93]
	v_mfma_f32_16x16x32_bf16 v[78:81], v[144:147], v[218:221], v[78:81]
	v_mfma_f32_16x16x32_bf16 v[74:77], v[152:155], v[218:221], v[74:77]
	v_mfma_f32_16x16x32_bf16 v[126:129], v[148:151], v[196:199], v[126:129]
	v_mfma_f32_16x16x32_bf16 v[122:125], v[172:175], v[196:199], v[122:125]
	v_mfma_f32_16x16x32_bf16 v[110:113], v[148:151], v[204:207], v[110:113]
	v_mfma_f32_16x16x32_bf16 v[106:109], v[172:175], v[204:207], v[106:109]
	v_mfma_f32_16x16x32_bf16 v[94:97], v[148:151], v[214:217], v[94:97]
	v_mfma_f32_16x16x32_bf16 v[90:93], v[172:175], v[214:217], v[90:93]
	v_mfma_f32_16x16x32_bf16 v[78:81], v[148:151], v[222:225], v[78:81]
	v_mfma_f32_16x16x32_bf16 v[74:77], v[172:175], v[222:225], v[74:77]
	v_mfma_f32_16x16x32_bf16 v[118:121], v[176:179], v[192:195], v[118:121]
	v_mfma_f32_16x16x32_bf16 v[114:117], v[184:187], v[192:195], v[114:117]
	v_mfma_f32_16x16x32_bf16 v[102:105], v[176:179], v[200:203], v[102:105]
	v_mfma_f32_16x16x32_bf16 v[98:101], v[184:187], v[200:203], v[98:101]
	v_mfma_f32_16x16x32_bf16 v[86:89], v[176:179], v[210:213], v[86:89]
	v_mfma_f32_16x16x32_bf16 v[82:85], v[184:187], v[210:213], v[82:85]
	v_mfma_f32_16x16x32_bf16 v[70:73], v[176:179], v[218:221], v[70:73]
	v_mfma_f32_16x16x32_bf16 v[66:69], v[184:187], v[218:221], v[66:69]
	v_mfma_f32_16x16x32_bf16 v[118:121], v[180:183], v[196:199], v[118:121]
	v_mfma_f32_16x16x32_bf16 v[114:117], v[188:191], v[196:199], v[114:117]
	v_mfma_f32_16x16x32_bf16 v[102:105], v[180:183], v[204:207], v[102:105]
	v_mfma_f32_16x16x32_bf16 v[98:101], v[188:191], v[204:207], v[98:101]
	v_mfma_f32_16x16x32_bf16 v[86:89], v[180:183], v[214:217], v[86:89]
	v_mfma_f32_16x16x32_bf16 v[82:85], v[188:191], v[214:217], v[82:85]
	v_mfma_f32_16x16x32_bf16 v[70:73], v[180:183], v[222:225], v[70:73]
	v_mfma_f32_16x16x32_bf16 v[66:69], v[188:191], v[222:225], v[66:69]
	s_setprio 0
	s_barrier
; #define PG8_STAGE(bufoff, gbase, voff) do { _Pragma("unroll") for (int _i = 0; _i < 2; ++_i) \
;         __builtin_amdgcn_global_load_lds((const unsigned*)((const char*)(gbase) + (voff)[_i]), (PG8_LAS unsigned*)(lds + (bufoff) + ldsw + _i * 8192), 16, 0, 0); } while (0)
; #define PG8_LDA(dst, b, h) do { _Pragma("unroll") for (int m = 0; m < 4; ++m) _Pragma("unroll") for (int k = 0; k < 2; ++k) dst[m][k] = *(const PG8_LAS bf16x8*)(lds + PG8_SA(b, h) + aoff + m * 2048 + k * 1024); } while (0)
; #define PG8_MMA(ai, bj, At, Bt) do { __builtin_amdgcn_s_setprio(1); _Pragma("unroll") for (int m = 0; m < 4; ++m) _Pragma("unroll") for (int n = 0; n < 2; ++n) _Pragma("unroll") for (int k = 0; k < 2; ++k) \
;         acc[ai][bj][m][n] = __builtin_amdgcn_mfma_f32_16x16x32_bf16(Bt[n][k], At[m][k], acc[ai][bj][m][n], 0, 0, 0); __builtin_amdgcn_s_setprio(0); } while (0)
; #define PG8_WAIT_V(n) asm volatile("s_waitcnt vmcnt(" #n ")" ::: "memory")
; #define PG8_WAIT_L(n) asm volatile("s_waitcnt lgkmcnt(" #n ")" ::: "memory")
; #define PG8_BAR __builtin_amdgcn_s_barrier()
; #define PG8_SCHED __builtin_amdgcn_sched_barrier(0)
; template <class Epi, class Sched, bool ALIGN_EPI = false, bool SP2 = false>
; __device__ __forceinline__ void gemm_phase(PG8_LAS unsigned char* lds, const Gemm g, const Sched& S, const Epi& E) {
;     ...
;             PG8_LDA(At, 1, 1); PG8_STAGE(PG8_SB(1, 0), b3, voffB); PG8_STAGE(PG8_SB(1, 1), b3 + hstep, voffB); PG8_STAGE(PG8_SA(1, 0), a3, voffA);
;             PG8_WAIT_V(8); PG8_WAIT_L(0); PG8_BAR; PG8_MMA(1, 0, At, B0); PG8_MMA(1, 1, At, B1); PG8_BAR; PG8_SCHED;
;     ...
;         if constexpr (ALIGN_EPI) { if (wr == 0) PG8_BAR; }
	s_add_i32 s0, s69, s39
	v_lshl_add_u64 v[226:227], v[226:227], 0, s[12:13]
	s_mov_b32 m0, s0
	ds_read_b128 v[192:195], v168 offset:49152
	ds_read_b128 v[196:199], v168 offset:50176
	ds_read_b128 v[200:203], v168 offset:51200
	ds_read_b128 v[204:207], v168 offset:52224
	ds_read_b128 v[210:213], v168 offset:53248
	ds_read_b128 v[214:217], v168 offset:54272
	ds_read_b128 v[218:221], v168 offset:55296
	ds_read_b128 v[222:225], v168 offset:56320
	global_load_lds_dwordx4 v[226:227], off
	s_add_i32 m0, s0, 0x2000
	s_add_u32 s0, s34, 0x40080
	v_lshl_add_u64 v[226:227], v[228:229], 0, s[12:13]
	s_addc_u32 s1, s35, 0
	s_add_i32 s34, s82, s39
	global_load_lds_dwordx4 v[226:227], off
	v_lshl_add_u64 v[226:227], s[0:1], 0, v[132:133]
	s_mov_b32 m0, s34
	s_nop 0
	global_load_lds_dwordx4 v[226:227], off
	v_lshl_add_u64 v[226:227], s[0:1], 0, v[136:137]
	s_add_i32 m0, s34, 0x2000
	s_nop 0
	global_load_lds_dwordx4 v[226:227], off
	v_lshl_add_u64 v[226:227], v[230:231], 0, s[12:13]
	s_mov_b32 m0, s54
	s_nop 0
	global_load_lds_dwordx4 v[226:227], off
	v_lshl_add_u64 v[226:227], v[232:233], 0, s[12:13]
	s_mov_b32 m0, s55
	s_nop 0
	global_load_lds_dwordx4 v[226:227], off
	s_waitcnt vmcnt(8)
	s_waitcnt lgkmcnt(0)
	s_barrier
	s_setprio 1
	s_waitcnt lgkmcnt(0)
	v_mfma_f32_16x16x32_bf16 v[62:65], v[144:147], v[192:195], v[62:65]
	v_mfma_f32_16x16x32_bf16 v[58:61], v[152:155], v[192:195], v[58:61]
	v_mfma_f32_16x16x32_bf16 v[46:49], v[144:147], v[200:203], v[46:49]
	v_mfma_f32_16x16x32_bf16 v[42:45], v[152:155], v[200:203], v[42:45]
	v_mfma_f32_16x16x32_bf16 v[30:33], v[144:147], v[210:213], v[30:33]
	v_mfma_f32_16x16x32_bf16 v[26:29], v[152:155], v[210:213], v[26:29]
	v_mfma_f32_16x16x32_bf16 v[14:17], v[144:147], v[218:221], v[14:17]
	v_mfma_f32_16x16x32_bf16 v[10:13], v[152:155], v[218:221], v[10:13]
	v_mfma_f32_16x16x32_bf16 v[62:65], v[148:151], v[196:199], v[62:65]
	v_mfma_f32_16x16x32_bf16 v[58:61], v[172:175], v[196:199], v[58:61]
	v_mfma_f32_16x16x32_bf16 v[46:49], v[148:151], v[204:207], v[46:49]
	v_mfma_f32_16x16x32_bf16 v[42:45], v[172:175], v[204:207], v[42:45]
	v_mfma_f32_16x16x32_bf16 v[30:33], v[148:151], v[214:217], v[30:33]
	v_mfma_f32_16x16x32_bf16 v[26:29], v[172:175], v[214:217], v[26:29]
	v_mfma_f32_16x16x32_bf16 v[14:17], v[148:151], v[222:225], v[14:17]
	v_mfma_f32_16x16x32_bf16 v[10:13], v[172:175], v[222:225], v[10:13]
	v_mfma_f32_16x16x32_bf16 v[54:57], v[176:179], v[192:195], v[54:57]
	v_mfma_f32_16x16x32_bf16 v[50:53], v[184:187], v[192:195], v[50:53]
	v_mfma_f32_16x16x32_bf16 v[38:41], v[176:179], v[200:203], v[38:41]
	v_mfma_f32_16x16x32_bf16 v[34:37], v[184:187], v[200:203], v[34:37]
	v_mfma_f32_16x16x32_bf16 v[22:25], v[176:179], v[210:213], v[22:25]
	v_mfma_f32_16x16x32_bf16 v[18:21], v[184:187], v[210:213], v[18:21]
	v_mfma_f32_16x16x32_bf16 v[6:9], v[176:179], v[218:221], v[6:9]
	v_mfma_f32_16x16x32_bf16 v[2:5], v[184:187], v[218:221], v[2:5]
	v_mfma_f32_16x16x32_bf16 v[54:57], v[180:183], v[196:199], v[54:57]
	v_mfma_f32_16x16x32_bf16 v[50:53], v[188:191], v[196:199], v[50:53]
	v_mfma_f32_16x16x32_bf16 v[38:41], v[180:183], v[204:207], v[38:41]
	v_mfma_f32_16x16x32_bf16 v[34:37], v[188:191], v[204:207], v[34:37]
	v_mfma_f32_16x16x32_bf16 v[22:25], v[180:183], v[214:217], v[22:25]
	v_mfma_f32_16x16x32_bf16 v[18:21], v[188:191], v[214:217], v[18:21]
	v_mfma_f32_16x16x32_bf16 v[6:9], v[180:183], v[222:225], v[6:9]
	v_mfma_f32_16x16x32_bf16 v[2:5], v[188:191], v[222:225], v[2:5]
	s_setprio 0
	s_barrier
	s_add_i32 s76, s76, 2
	s_add_u32 s30, s30, 0x100
	s_addc_u32 s31, s31, 0
	s_add_u32 s72, s72, 0x100
	s_addc_u32 s73, s73, 0
	s_cmp_gt_u32 s76, 13
	s_cbranch_scc0 .LBB0_1230
	s_and_b64 vcc, exec, s[14:15]
	s_cbranch_vccz .LBB0_1233
	s_barrier

; #define PG8_STAGE(bufoff, gbase, voff) do { _Pragma("unroll") for (int _i = 0; _i < 2; ++_i) \
;         __builtin_amdgcn_global_load_lds((const unsigned*)((const char*)(gbase) + (voff)[_i]), (PG8_LAS unsigned*)(lds + (bufoff) + ldsw + _i * 8192), 16, 0, 0); } while (0)
; #define PG8_LDA(dst, b, h) do { _Pragma("unroll") for (int m = 0; m < 4; ++m) _Pragma("unroll") for (int k = 0; k < 2; ++k) dst[m][k] = *(const PG8_LAS bf16x8*)(lds + PG8_SA(b, h) + aoff + m * 2048 + k * 1024); } while (0)
; #define PG8_LDB(dst, b, h) do { _Pragma("unroll") for (int n = 0; n < 2; ++n) _Pragma("unroll") for (int k = 0; k < 2; ++k) dst[n][k] = *(const PG8_LAS bf16x8*)(lds + PG8_SB(b, h) + boff + n * 2048 + k * 1024); } while (0)
; #define PG8_MMA(ai, bj, At, Bt) do { __builtin_amdgcn_s_setprio(1); _Pragma("unroll") for (int m = 0; m < 4; ++m) _Pragma("unroll") for (int n = 0; n < 2; ++n) _Pragma("unroll") for (int k = 0; k < 2; ++k) \
;         acc[ai][bj][m][n] = __builtin_amdgcn_mfma_f32_16x16x32_bf16(Bt[n][k], At[m][k], acc[ai][bj][m][n], 0, 0, 0); __builtin_amdgcn_s_setprio(0); } while (0)
; #define PG8_WAIT_V(n) asm volatile("s_waitcnt vmcnt(" #n ")" ::: "memory")
; #define PG8_WAIT_L(n) asm volatile("s_waitcnt lgkmcnt(" #n ")" ::: "memory")
; #define PG8_BAR __builtin_amdgcn_s_barrier()
; #define PG8_SCHED __builtin_amdgcn_sched_barrier(0)
; template <class Epi, class Sched, bool ALIGN_EPI = false, bool SP2 = false>
; __device__ __forceinline__ void gemm_phase(PG8_LAS unsigned char* lds, const Gemm g, const Sched& S, const Epi& E) {
;     ...
;             const bool last = (t == nt - 2);
;             const char* a1 = cA + (size_t)(t + 1) * kstep;
;             const char* a2 = last ? nA : cA + (size_t)(t + 2) * kstep; const char* b2 = last ? nB : cB + (size_t)(t + 2) * kstep;
;             const char* a3 = a2 + kstep; const char* b3 = b2 + kstep;
;             if (last && has_next) S.a_ready(nxt);
;             if constexpr (SP2) {
;             PG8_LDB(B0, 0, 0); PG8_LDB(B1, 0, 1); PG8_SCHED; PG8_LDA(At, 0, 0); PG8_STAGE(PG8_SA(1, 1), a1 + hstep, voffA);
;             PG8_WAIT_V(8); PG8_WAIT_L(0); PG8_BAR; PG8_MMA(0, 0, At, B0); PG8_MMA(0, 1, At, B1); PG8_BAR; PG8_SCHED;
;             PG8_LDA(At, 0, 1); PG8_STAGE(PG8_SB(0, 0), b2, voffB); PG8_STAGE(PG8_SB(0, 1), b2 + hstep, voffB); PG8_STAGE(PG8_SA(0, 0), a2, voffA);
.LBB0_1267:
	ds_read_b128 v[144:147], v1
	ds_read_b128 v[156:159], v1 offset:1024
	ds_read_b128 v[160:163], v1 offset:2048
	ds_read_b128 v[164:167], v1 offset:3072
	ds_read_b128 v[168:171], v150
	ds_read_b128 v[172:175], v150 offset:1024
	ds_read_b128 v[176:179], v150 offset:2048
	ds_read_b128 v[180:183], v150 offset:3072
	s_add_u32 s0, s28, 0xfffc0080
	s_addc_u32 s1, s29, -1
	s_cmp_eq_u32 s73, 12
	s_cselect_b32 s35, s19, s1
	s_cselect_b32 s34, s27, s0
	s_cselect_b32 s31, s17, s72
	s_cselect_b32 s30, s59, s69
	v_lshl_add_u64 v[218:219], s[28:29], 0, v[138:139]
	s_add_i32 m0, s37, 0xc000
	ds_read_b128 v[184:187], v151
	ds_read_b128 v[188:191], v151 offset:1024
	ds_read_b128 v[192:195], v151 offset:2048
	ds_read_b128 v[196:199], v151 offset:3072
	ds_read_b128 v[200:203], v151 offset:4096
	ds_read_b128 v[204:207], v151 offset:5120
	ds_read_b128 v[210:213], v151 offset:6144
	ds_read_b128 v[214:217], v151 offset:7168
	global_load_lds_dwordx4 v[218:219], off
	v_lshl_add_u64 v[218:219], s[28:29], 0, v[140:141]
	s_add_i32 m0, s37, 0xe000
	s_nop 0
	global_load_lds_dwordx4 v[218:219], off
	s_waitcnt vmcnt(8)
	s_waitcnt lgkmcnt(0)
	s_barrier
	s_setprio 1
	s_waitcnt lgkmcnt(0)
	v_mfma_f32_16x16x32_bf16 v[126:129], v[144:147], v[184:187], v[126:129]
	v_mfma_f32_16x16x32_bf16 v[122:125], v[160:163], v[184:187], v[122:125]
	v_mfma_f32_16x16x32_bf16 v[110:113], v[144:147], v[192:195], v[110:113]
	v_mfma_f32_16x16x32_bf16 v[106:109], v[160:163], v[192:195], v[106:109]
	v_mfma_f32_16x16x32_bf16 v[94:97], v[144:147], v[200:203], v[94:97]
	v_mfma_f32_16x16x32_bf16 v[90:93], v[160:163], v[200:203], v[90:93]
	v_mfma_f32_16x16x32_bf16 v[78:81], v[144:147], v[210:213], v[78:81]
	v_mfma_f32_16x16x32_bf16 v[74:77], v[160:163], v[210:213], v[74:77]
	v_mfma_f32_16x16x32_bf16 v[126:129], v[156:159], v[188:191], v[126:129]
	v_mfma_f32_16x16x32_bf16 v[122:125], v[164:167], v[188:191], v[122:125]
	v_mfma_f32_16x16x32_bf16 v[110:113], v[156:159], v[196:199], v[110:113]
	v_mfma_f32_16x16x32_bf16 v[106:109], v[164:167], v[196:199], v[106:109]
	v_mfma_f32_16x16x32_bf16 v[94:97], v[156:159], v[204:207], v[94:97]
	v_mfma_f32_16x16x32_bf16 v[90:93], v[164:167], v[204:207], v[90:93]
	v_mfma_f32_16x16x32_bf16 v[78:81], v[156:159], v[214:217], v[78:81]
	v_mfma_f32_16x16x32_bf16 v[74:77], v[164:167], v[214:217], v[74:77]
	v_mfma_f32_16x16x32_bf16 v[118:121], v[168:171], v[184:187], v[118:121]
	v_mfma_f32_16x16x32_bf16 v[114:117], v[176:179], v[184:187], v[114:117]
	v_mfma_f32_16x16x32_bf16 v[102:105], v[168:171], v[192:195], v[102:105]
	v_mfma_f32_16x16x32_bf16 v[98:101], v[176:179], v[192:195], v[98:101]
	v_mfma_f32_16x16x32_bf16 v[86:89], v[168:171], v[200:203], v[86:89]
	v_mfma_f32_16x16x32_bf16 v[82:85], v[176:179], v[200:203], v[82:85]
	v_mfma_f32_16x16x32_bf16 v[70:73], v[168:171], v[210:213], v[70:73]
	v_mfma_f32_16x16x32_bf16 v[66:69], v[176:179], v[210:213], v[66:69]
	v_mfma_f32_16x16x32_bf16 v[118:121], v[172:175], v[188:191], v[118:121]
	v_mfma_f32_16x16x32_bf16 v[114:117], v[180:183], v[188:191], v[114:117]
	v_mfma_f32_16x16x32_bf16 v[102:105], v[172:175], v[196:199], v[102:105]
	v_mfma_f32_16x16x32_bf16 v[98:101], v[180:183], v[196:199], v[98:101]
	v_mfma_f32_16x16x32_bf16 v[86:89], v[172:175], v[204:207], v[86:89]
	v_mfma_f32_16x16x32_bf16 v[82:85], v[180:183], v[204:207], v[82:85]
	v_mfma_f32_16x16x32_bf16 v[70:73], v[172:175], v[214:217], v[70:73]
	v_mfma_f32_16x16x32_bf16 v[66:69], v[180:183], v[214:217], v[66:69]
	s_setprio 0
	s_barrier
	s_add_i32 s0, s54, s36
	v_lshl_add_u64 v[218:219], s[30:31], 0, v[132:133]
	s_mov_b32 m0, s0
	ds_read_b128 v[184:187], v151 offset:16384
	ds_read_b128 v[188:191], v151 offset:17408
	ds_read_b128 v[192:195], v151 offset:18432
	ds_read_b128 v[196:199], v151 offset:19456
	ds_read_b128 v[200:203], v151 offset:20480
	ds_read_b128 v[204:207], v151 offset:21504
	ds_read_b128 v[210:213], v151 offset:22528
	ds_read_b128 v[214:217], v151 offset:23552
	global_load_lds_dwordx4 v[218:219], off
	s_add_i32 m0, s0, 0x2000
	s_add_u32 s0, s30, 0x40000
	v_lshl_add_u64 v[220:221], s[30:31], 0, v[136:137]
	s_addc_u32 s1, s31, 0
	s_add_i32 s76, s55, s36
	global_load_lds_dwordx4 v[220:221], off
	v_lshl_add_u64 v[222:223], s[0:1], 0, v[132:133]
	s_mov_b32 m0, s76
	v_lshl_add_u64 v[224:225], s[34:35], 0, v[134:135]
	global_load_lds_dwordx4 v[222:223], off
	v_lshl_add_u64 v[222:223], s[0:1], 0, v[136:137]
	s_add_i32 m0, s76, 0x2000
	s_nop 0
	global_load_lds_dwordx4 v[222:223], off
	v_lshl_add_u64 v[222:223], s[34:35], 0, v[130:131]
	s_mov_b32 m0, s37
	s_nop 0
	global_load_lds_dwordx4 v[222:223], off
	s_mov_b32 m0, s39
	s_nop 0
	global_load_lds_dwordx4 v[224:225], off
	s_waitcnt vmcnt(8)
	s_waitcnt lgkmcnt(0)
	s_barrier
; #define PG8_STAGE(bufoff, gbase, voff) do { _Pragma("unroll") for (int _i = 0; _i < 2; ++_i) \
;         __builtin_amdgcn_global_load_lds((const unsigned*)((const char*)(gbase) + (voff)[_i]), (PG8_LAS unsigned*)(lds + (bufoff) + ldsw + _i * 8192), 16, 0, 0); } while (0)
; #define PG8_LDA(dst, b, h) do { _Pragma("unroll") for (int m = 0; m < 4; ++m) _Pragma("unroll") for (int k = 0; k < 2; ++k) dst[m][k] = *(const PG8_LAS bf16x8*)(lds + PG8_SA(b, h) + aoff + m * 2048 + k * 1024); } while (0)
; #define PG8_LDB(dst, b, h) do { _Pragma("unroll") for (int n = 0; n < 2; ++n) _Pragma("unroll") for (int k = 0; k < 2; ++k) dst[n][k] = *(const PG8_LAS bf16x8*)(lds + PG8_SB(b, h) + boff + n * 2048 + k * 1024); } while (0)
; #define PG8_MMA(ai, bj, At, Bt) do { __builtin_amdgcn_s_setprio(1); _Pragma("unroll") for (int m = 0; m < 4; ++m) _Pragma("unroll") for (int n = 0; n < 2; ++n) _Pragma("unroll") for (int k = 0; k < 2; ++k) \
;         acc[ai][bj][m][n] = __builtin_amdgcn_mfma_f32_16x16x32_bf16(Bt[n][k], At[m][k], acc[ai][bj][m][n], 0, 0, 0); __builtin_amdgcn_s_setprio(0); } while (0)
; #define PG8_WAIT_V(n) asm volatile("s_waitcnt vmcnt(" #n ")" ::: "memory")
; #define PG8_WAIT_L(n) asm volatile("s_waitcnt lgkmcnt(" #n ")" ::: "memory")
; #define PG8_BAR __builtin_amdgcn_s_barrier()
; #define PG8_SCHED __builtin_amdgcn_sched_barrier(0)
; template <class Epi, class Sched, bool ALIGN_EPI = false, bool SP2 = false>
; __device__ __forceinline__ void gemm_phase(PG8_LAS unsigned char* lds, const Gemm g, const Sched& S, const Epi& E) {
;     ...
;             PG8_WAIT_V(8); PG8_WAIT_L(0); PG8_BAR; PG8_MMA(1, 0, At, B0); PG8_MMA(1, 1, At, B1); PG8_BAR; PG8_SCHED;
;             PG8_LDB(B0, 1, 0); PG8_LDB(B1, 1, 1); PG8_SCHED; PG8_LDA(At, 1, 0); PG8_STAGE(PG8_SA(0, 1), a2 + hstep, voffA);
;             PG8_WAIT_V(8); PG8_WAIT_L(0); PG8_BAR; PG8_MMA(0, 0, At, B0); PG8_MMA(0, 1, At, B1); PG8_BAR; PG8_SCHED;
	s_setprio 1
	s_waitcnt lgkmcnt(0)
	v_mfma_f32_16x16x32_bf16 v[62:65], v[144:147], v[184:187], v[62:65]
	v_mfma_f32_16x16x32_bf16 v[58:61], v[160:163], v[184:187], v[58:61]
	v_mfma_f32_16x16x32_bf16 v[46:49], v[144:147], v[192:195], v[46:49]
	v_mfma_f32_16x16x32_bf16 v[42:45], v[160:163], v[192:195], v[42:45]
	v_mfma_f32_16x16x32_bf16 v[30:33], v[144:147], v[200:203], v[30:33]
	v_mfma_f32_16x16x32_bf16 v[26:29], v[160:163], v[200:203], v[26:29]
	v_mfma_f32_16x16x32_bf16 v[14:17], v[144:147], v[210:213], v[14:17]
	v_mfma_f32_16x16x32_bf16 v[10:13], v[160:163], v[210:213], v[10:13]
	v_mfma_f32_16x16x32_bf16 v[62:65], v[156:159], v[188:191], v[62:65]
	v_mfma_f32_16x16x32_bf16 v[58:61], v[164:167], v[188:191], v[58:61]
	v_mfma_f32_16x16x32_bf16 v[46:49], v[156:159], v[196:199], v[46:49]
	v_mfma_f32_16x16x32_bf16 v[42:45], v[164:167], v[196:199], v[42:45]
	v_mfma_f32_16x16x32_bf16 v[30:33], v[156:159], v[204:207], v[30:33]
	v_mfma_f32_16x16x32_bf16 v[26:29], v[164:167], v[204:207], v[26:29]
	v_mfma_f32_16x16x32_bf16 v[14:17], v[156:159], v[214:217], v[14:17]
	v_mfma_f32_16x16x32_bf16 v[10:13], v[164:167], v[214:217], v[10:13]
	v_mfma_f32_16x16x32_bf16 v[54:57], v[168:171], v[184:187], v[54:57]
	v_mfma_f32_16x16x32_bf16 v[50:53], v[176:179], v[184:187], v[50:53]
	v_mfma_f32_16x16x32_bf16 v[38:41], v[168:171], v[192:195], v[38:41]
	v_mfma_f32_16x16x32_bf16 v[34:37], v[176:179], v[192:195], v[34:37]
	v_mfma_f32_16x16x32_bf16 v[22:25], v[168:171], v[200:203], v[22:25]
	v_mfma_f32_16x16x32_bf16 v[18:21], v[176:179], v[200:203], v[18:21]
	v_mfma_f32_16x16x32_bf16 v[6:9], v[168:171], v[210:213], v[6:9]
	v_mfma_f32_16x16x32_bf16 v[2:5], v[176:179], v[210:213], v[2:5]
	v_mfma_f32_16x16x32_bf16 v[54:57], v[172:175], v[188:191], v[54:57]
	v_mfma_f32_16x16x32_bf16 v[50:53], v[180:183], v[188:191], v[50:53]
	v_mfma_f32_16x16x32_bf16 v[38:41], v[172:175], v[196:199], v[38:41]
	v_mfma_f32_16x16x32_bf16 v[34:37], v[180:183], v[196:199], v[34:37]
	v_mfma_f32_16x16x32_bf16 v[22:25], v[172:175], v[204:207], v[22:25]
	v_mfma_f32_16x16x32_bf16 v[18:21], v[180:183], v[204:207], v[18:21]
	v_mfma_f32_16x16x32_bf16 v[6:9], v[172:175], v[214:217], v[6:9]
	v_mfma_f32_16x16x32_bf16 v[2:5], v[180:183], v[214:217], v[2:5]
	s_setprio 0
	s_barrier
	ds_read_b128 v[144:147], v153
	ds_read_b128 v[156:159], v153 offset:1024
	ds_read_b128 v[160:163], v153 offset:2048
	ds_read_b128 v[164:167], v153 offset:3072
	ds_read_b128 v[168:171], v154
	ds_read_b128 v[172:175], v154 offset:1024
	ds_read_b128 v[176:179], v154 offset:2048
	ds_read_b128 v[180:183], v154 offset:3072
	s_add_u32 s0, s34, 0x40000
	s_addc_u32 s1, s35, 0
	s_mov_b32 m0, s40
	v_lshl_add_u64 v[226:227], s[0:1], 0, v[130:131]
	ds_read_b128 v[184:187], v151 offset:32768
	ds_read_b128 v[188:191], v151 offset:33792
	ds_read_b128 v[192:195], v151 offset:34816
	ds_read_b128 v[196:199], v151 offset:35840
	ds_read_b128 v[200:203], v151 offset:36864
	ds_read_b128 v[204:207], v151 offset:37888
	ds_read_b128 v[210:213], v151 offset:38912
	ds_read_b128 v[214:217], v151 offset:39936
	global_load_lds_dwordx4 v[226:227], off
	v_lshl_add_u64 v[226:227], s[0:1], 0, v[134:135]
	s_mov_b32 m0, s41
	s_nop 0
	global_load_lds_dwordx4 v[226:227], off
	s_waitcnt vmcnt(8)
	s_waitcnt lgkmcnt(0)
	s_barrier
	s_setprio 1
	s_waitcnt lgkmcnt(0)
	v_mfma_f32_16x16x32_bf16 v[126:129], v[144:147], v[184:187], v[126:129]
	v_mfma_f32_16x16x32_bf16 v[122:125], v[160:163], v[184:187], v[122:125]
	v_mfma_f32_16x16x32_bf16 v[110:113], v[144:147], v[192:195], v[110:113]
	v_mfma_f32_16x16x32_bf16 v[106:109], v[160:163], v[192:195], v[106:109]
	v_mfma_f32_16x16x32_bf16 v[94:97], v[144:147], v[200:203], v[94:97]
	v_mfma_f32_16x16x32_bf16 v[90:93], v[160:163], v[200:203], v[90:93]
	v_mfma_f32_16x16x32_bf16 v[78:81], v[144:147], v[210:213], v[78:81]
	v_mfma_f32_16x16x32_bf16 v[74:77], v[160:163], v[210:213], v[74:77]
	v_mfma_f32_16x16x32_bf16 v[126:129], v[156:159], v[188:191], v[126:129]
	v_mfma_f32_16x16x32_bf16 v[122:125], v[164:167], v[188:191], v[122:125]
	v_mfma_f32_16x16x32_bf16 v[110:113], v[156:159], v[196:199], v[110:113]
	v_mfma_f32_16x16x32_bf16 v[106:109], v[164:167], v[196:199], v[106:109]
	v_mfma_f32_16x16x32_bf16 v[94:97], v[156:159], v[204:207], v[94:97]
	v_mfma_f32_16x16x32_bf16 v[90:93], v[164:167], v[204:207], v[90:93]
	v_mfma_f32_16x16x32_bf16 v[78:81], v[156:159], v[214:217], v[78:81]
	v_mfma_f32_16x16x32_bf16 v[74:77], v[164:167], v[214:217], v[74:77]
	v_mfma_f32_16x16x32_bf16 v[118:121], v[168:171], v[184:187], v[118:121]
	v_mfma_f32_16x16x32_bf16 v[114:117], v[176:179], v[184:187], v[114:117]
	v_mfma_f32_16x16x32_bf16 v[102:105], v[168:171], v[192:195], v[102:105]
	v_mfma_f32_16x16x32_bf16 v[98:101], v[176:179], v[192:195], v[98:101]
	v_mfma_f32_16x16x32_bf16 v[86:89], v[168:171], v[200:203], v[86:89]
	v_mfma_f32_16x16x32_bf16 v[82:85], v[176:179], v[200:203], v[82:85]
	v_mfma_f32_16x16x32_bf16 v[70:73], v[168:171], v[210:213], v[70:73]
	v_mfma_f32_16x16x32_bf16 v[66:69], v[176:179], v[210:213], v[66:69]
	v_mfma_f32_16x16x32_bf16 v[118:121], v[172:175], v[188:191], v[118:121]
	v_mfma_f32_16x16x32_bf16 v[114:117], v[180:183], v[188:191], v[114:117]
	v_mfma_f32_16x16x32_bf16 v[102:105], v[172:175], v[196:199], v[102:105]
	v_mfma_f32_16x16x32_bf16 v[98:101], v[180:183], v[196:199], v[98:101]
	v_mfma_f32_16x16x32_bf16 v[86:89], v[172:175], v[204:207], v[86:89]
	v_mfma_f32_16x16x32_bf16 v[82:85], v[180:183], v[204:207], v[82:85]
	v_mfma_f32_16x16x32_bf16 v[70:73], v[172:175], v[214:217], v[70:73]
	v_mfma_f32_16x16x32_bf16 v[66:69], v[180:183], v[214:217], v[66:69]
	s_setprio 0
	s_barrier
; #define PG8_STAGE(bufoff, gbase, voff) do { _Pragma("unroll") for (int _i = 0; _i < 2; ++_i) \
;         __builtin_amdgcn_global_load_lds((const unsigned*)((const char*)(gbase) + (voff)[_i]), (PG8_LAS unsigned*)(lds + (bufoff) + ldsw + _i * 8192), 16, 0, 0); } while (0)
; #define PG8_LDA(dst, b, h) do { _Pragma("unroll") for (int m = 0; m < 4; ++m) _Pragma("unroll") for (int k = 0; k < 2; ++k) dst[m][k] = *(const PG8_LAS bf16x8*)(lds + PG8_SA(b, h) + aoff + m * 2048 + k * 1024); } while (0)
; #define PG8_MMA(ai, bj, At, Bt) do { __builtin_amdgcn_s_setprio(1); _Pragma("unroll") for (int m = 0; m < 4; ++m) _Pragma("unroll") for (int n = 0; n < 2; ++n) _Pragma("unroll") for (int k = 0; k < 2; ++k) \
;         acc[ai][bj][m][n] = __builtin_amdgcn_mfma_f32_16x16x32_bf16(Bt[n][k], At[m][k], acc[ai][bj][m][n], 0, 0, 0); __builtin_amdgcn_s_setprio(0); } while (0)
; #define PG8_WAIT_V(n) asm volatile("s_waitcnt vmcnt(" #n ")" ::: "memory")
; #define PG8_WAIT_L(n) asm volatile("s_waitcnt lgkmcnt(" #n ")" ::: "memory")
; #define PG8_BAR __builtin_amdgcn_s_barrier()
; #define PG8_SCHED __builtin_amdgcn_sched_barrier(0)
; template <class Epi, class Sched, bool ALIGN_EPI = false, bool SP2 = false>
; __device__ __forceinline__ void gemm_phase(PG8_LAS unsigned char* lds, const Gemm g, const Sched& S, const Epi& E) {
;     ...
;             PG8_LDA(At, 1, 1); PG8_STAGE(PG8_SB(1, 0), b3, voffB); PG8_STAGE(PG8_SB(1, 1), b3 + hstep, voffB); PG8_STAGE(PG8_SA(1, 0), a3, voffA);
;             PG8_WAIT_V(8); PG8_WAIT_L(0); PG8_BAR; PG8_MMA(1, 0, At, B0); PG8_MMA(1, 1, At, B1); PG8_BAR; PG8_SCHED;
;     ...
;         if constexpr (ALIGN_EPI) { if (wr == 0) PG8_BAR; }
	s_add_i32 s0, s56, s36
	v_lshl_add_u64 v[218:219], v[218:219], 0, s[10:11]
	s_mov_b32 m0, s0
	ds_read_b128 v[184:187], v151 offset:49152
	ds_read_b128 v[188:191], v151 offset:50176
	ds_read_b128 v[192:195], v151 offset:51200
	ds_read_b128 v[196:199], v151 offset:52224
	ds_read_b128 v[200:203], v151 offset:53248
	ds_read_b128 v[204:207], v151 offset:54272
	ds_read_b128 v[210:213], v151 offset:55296
	ds_read_b128 v[214:217], v151 offset:56320
	global_load_lds_dwordx4 v[218:219], off
	s_add_i32 m0, s0, 0x2000
	s_add_u32 s0, s30, 0x40080
	v_lshl_add_u64 v[218:219], v[220:221], 0, s[10:11]
	s_addc_u32 s1, s31, 0
	s_add_i32 s30, s57, s36
	global_load_lds_dwordx4 v[218:219], off
	v_lshl_add_u64 v[218:219], s[0:1], 0, v[132:133]
	s_mov_b32 m0, s30
	s_nop 0
	global_load_lds_dwordx4 v[218:219], off
	v_lshl_add_u64 v[218:219], s[0:1], 0, v[136:137]
	s_add_i32 m0, s30, 0x2000
	s_nop 0
	global_load_lds_dwordx4 v[218:219], off
	v_lshl_add_u64 v[218:219], v[222:223], 0, s[10:11]
	s_mov_b32 m0, s48
	s_nop 0
	global_load_lds_dwordx4 v[218:219], off
	v_lshl_add_u64 v[218:219], v[224:225], 0, s[10:11]
	s_mov_b32 m0, s49
	s_nop 0
	global_load_lds_dwordx4 v[218:219], off
	s_waitcnt vmcnt(8)
	s_waitcnt lgkmcnt(0)
	s_barrier
	s_setprio 1
	s_waitcnt lgkmcnt(0)
	v_mfma_f32_16x16x32_bf16 v[62:65], v[144:147], v[184:187], v[62:65]
	v_mfma_f32_16x16x32_bf16 v[58:61], v[160:163], v[184:187], v[58:61]
	v_mfma_f32_16x16x32_bf16 v[46:49], v[144:147], v[192:195], v[46:49]
	v_mfma_f32_16x16x32_bf16 v[42:45], v[160:163], v[192:195], v[42:45]
	v_mfma_f32_16x16x32_bf16 v[30:33], v[144:147], v[200:203], v[30:33]
	v_mfma_f32_16x16x32_bf16 v[26:29], v[160:163], v[200:203], v[26:29]
	v_mfma_f32_16x16x32_bf16 v[14:17], v[144:147], v[210:213], v[14:17]
	v_mfma_f32_16x16x32_bf16 v[10:13], v[160:163], v[210:213], v[10:13]
	v_mfma_f32_16x16x32_bf16 v[62:65], v[156:159], v[188:191], v[62:65]
	v_mfma_f32_16x16x32_bf16 v[58:61], v[164:167], v[188:191], v[58:61]
	v_mfma_f32_16x16x32_bf16 v[46:49], v[156:159], v[196:199], v[46:49]
	v_mfma_f32_16x16x32_bf16 v[42:45], v[164:167], v[196:199], v[42:45]
	v_mfma_f32_16x16x32_bf16 v[30:33], v[156:159], v[204:207], v[30:33]
	v_mfma_f32_16x16x32_bf16 v[26:29], v[164:167], v[204:207], v[26:29]
	v_mfma_f32_16x16x32_bf16 v[14:17], v[156:159], v[214:217], v[14:17]
	v_mfma_f32_16x16x32_bf16 v[10:13], v[164:167], v[214:217], v[10:13]
	v_mfma_f32_16x16x32_bf16 v[54:57], v[168:171], v[184:187], v[54:57]
	v_mfma_f32_16x16x32_bf16 v[50:53], v[176:179], v[184:187], v[50:53]
	v_mfma_f32_16x16x32_bf16 v[38:41], v[168:171], v[192:195], v[38:41]
	v_mfma_f32_16x16x32_bf16 v[34:37], v[176:179], v[192:195], v[34:37]
	v_mfma_f32_16x16x32_bf16 v[22:25], v[168:171], v[200:203], v[22:25]
	v_mfma_f32_16x16x32_bf16 v[18:21], v[176:179], v[200:203], v[18:21]
	v_mfma_f32_16x16x32_bf16 v[6:9], v[168:171], v[210:213], v[6:9]
	v_mfma_f32_16x16x32_bf16 v[2:5], v[176:179], v[210:213], v[2:5]
	v_mfma_f32_16x16x32_bf16 v[54:57], v[172:175], v[188:191], v[54:57]
	v_mfma_f32_16x16x32_bf16 v[50:53], v[180:183], v[188:191], v[50:53]
	v_mfma_f32_16x16x32_bf16 v[38:41], v[172:175], v[196:199], v[38:41]
	v_mfma_f32_16x16x32_bf16 v[34:37], v[180:183], v[196:199], v[34:37]
	v_mfma_f32_16x16x32_bf16 v[22:25], v[172:175], v[204:207], v[22:25]
	v_mfma_f32_16x16x32_bf16 v[18:21], v[180:183], v[204:207], v[18:21]
	v_mfma_f32_16x16x32_bf16 v[6:9], v[172:175], v[214:217], v[6:9]
	v_mfma_f32_16x16x32_bf16 v[2:5], v[180:183], v[214:217], v[2:5]
	s_setprio 0
	s_barrier
	s_add_i32 s73, s73, 2
	s_add_u32 s28, s28, 0x100
	s_addc_u32 s29, s29, 0
	s_add_u32 s69, s69, 0x100
	s_addc_u32 s72, s72, 0
	s_cmp_gt_u32 s73, 13
	s_cbranch_scc0 .LBB0_1267
	s_and_b64 vcc, exec, s[12:13]
	s_cbranch_vccz .LBB0_1270
	s_barrier

; #define PG8_STAGE(bufoff, gbase, voff) do { _Pragma("unroll") for (int _i = 0; _i < 2; ++_i) \
;         __builtin_amdgcn_global_load_lds((const unsigned*)((const char*)(gbase) + (voff)[_i]), (PG8_LAS unsigned*)(lds + (bufoff) + ldsw + _i * 8192), 16, 0, 0); } while (0)
; #define PG8_LDA(dst, b, h) do { _Pragma("unroll") for (int m = 0; m < 4; ++m) _Pragma("unroll") for (int k = 0; k < 2; ++k) dst[m][k] = *(const PG8_LAS bf16x8*)(lds + PG8_SA(b, h) + aoff + m * 2048 + k * 1024); } while (0)
; #define PG8_LDB(dst, b, h) do { _Pragma("unroll") for (int n = 0; n < 2; ++n) _Pragma("unroll") for (int k = 0; k < 2; ++k) dst[n][k] = *(const PG8_LAS bf16x8*)(lds + PG8_SB(b, h) + boff + n * 2048 + k * 1024); } while (0)
; #define PG8_MMA(ai, bj, At, Bt) do { __builtin_amdgcn_s_setprio(1); _Pragma("unroll") for (int m = 0; m < 4; ++m) _Pragma("unroll") for (int n = 0; n < 2; ++n) _Pragma("unroll") for (int k = 0; k < 2; ++k) \
;         acc[ai][bj][m][n] = __builtin_amdgcn_mfma_f32_16x16x32_bf16(Bt[n][k], At[m][k], acc[ai][bj][m][n], 0, 0, 0); __builtin_amdgcn_s_setprio(0); } while (0)
; #define PG8_WAIT_V(n) asm volatile("s_waitcnt vmcnt(" #n ")" ::: "memory")
; #define PG8_WAIT_L(n) asm volatile("s_waitcnt lgkmcnt(" #n ")" ::: "memory")
; #define PG8_BAR __builtin_amdgcn_s_barrier()
; #define PG8_SCHED __builtin_amdgcn_sched_barrier(0)
; template <class Epi, class Sched, bool ALIGN_EPI = false, bool SP2 = false>
; __device__ __forceinline__ void gemm_phase(PG8_LAS unsigned char* lds, const Gemm g, const Sched& S, const Epi& E) {
;     ...
;             const bool last = (t == nt - 2);
;             const char* a1 = cA + (size_t)(t + 1) * kstep;
;             const char* a2 = last ? nA : cA + (size_t)(t + 2) * kstep; const char* b2 = last ? nB : cB + (size_t)(t + 2) * kstep;
;             const char* a3 = a2 + kstep; const char* b3 = b2 + kstep;
;             if (last && has_next) S.a_ready(nxt);
;             if constexpr (SP2) {
;             PG8_LDB(B0, 0, 0); PG8_LDB(B1, 0, 1); PG8_SCHED; PG8_LDA(At, 0, 0); PG8_STAGE(PG8_SA(1, 1), a1 + hstep, voffA);
;             PG8_WAIT_V(8); PG8_WAIT_L(0); PG8_BAR; PG8_MMA(0, 0, At, B0); PG8_MMA(0, 1, At, B1); PG8_BAR; PG8_SCHED;
;             PG8_LDA(At, 0, 1); PG8_STAGE(PG8_SB(0, 0), b2, voffB); PG8_STAGE(PG8_SB(0, 1), b2 + hstep, voffB); PG8_STAGE(PG8_SA(0, 0), a2, voffA);
.LBB0_1380:
	ds_read_b128 v[146:149], v153
	ds_read_b128 v[160:163], v153 offset:1024
	ds_read_b128 v[164:167], v153 offset:2048
	ds_read_b128 v[168:171], v153 offset:3072
	ds_read_b128 v[172:175], v154
	ds_read_b128 v[176:179], v154 offset:1024
	ds_read_b128 v[180:183], v154 offset:2048
	ds_read_b128 v[184:187], v154 offset:3072
	s_add_u32 s0, s4, 0xfffc0080
	s_addc_u32 s1, s5, -1
	s_cmp_eq_u32 s54, 12
	s_cselect_b32 s29, s15, s1
	s_cselect_b32 s28, s25, s0
	s_cselect_b32 s27, s9, s53
	s_cselect_b32 s26, s49, s52
	v_lshl_add_u64 v[222:223], s[4:5], 0, v[140:141]
	s_add_i32 m0, s34, 0xc000
	ds_read_b128 v[188:191], v155
	ds_read_b128 v[192:195], v155 offset:1024
	ds_read_b128 v[196:199], v155 offset:2048
	ds_read_b128 v[200:203], v155 offset:3072
	ds_read_b128 v[204:207], v155 offset:4096
	ds_read_b128 v[210:213], v155 offset:5120
	ds_read_b128 v[214:217], v155 offset:6144
	ds_read_b128 v[218:221], v155 offset:7168
	global_load_lds_dwordx4 v[222:223], off
	v_lshl_add_u64 v[222:223], s[4:5], 0, v[142:143]
	s_add_i32 m0, s34, 0xe000
	s_nop 0
	global_load_lds_dwordx4 v[222:223], off
	s_waitcnt vmcnt(8)
	s_waitcnt lgkmcnt(0)
	s_barrier
	s_setprio 1
	s_waitcnt lgkmcnt(0)
	v_mfma_f32_16x16x32_bf16 v[126:129], v[146:149], v[188:191], v[126:129]
	v_mfma_f32_16x16x32_bf16 v[122:125], v[164:167], v[188:191], v[122:125]
	v_mfma_f32_16x16x32_bf16 v[110:113], v[146:149], v[196:199], v[110:113]
	v_mfma_f32_16x16x32_bf16 v[106:109], v[164:167], v[196:199], v[106:109]
	v_mfma_f32_16x16x32_bf16 v[94:97], v[146:149], v[204:207], v[94:97]
	v_mfma_f32_16x16x32_bf16 v[90:93], v[164:167], v[204:207], v[90:93]
	v_mfma_f32_16x16x32_bf16 v[78:81], v[146:149], v[214:217], v[78:81]
	v_mfma_f32_16x16x32_bf16 v[74:77], v[164:167], v[214:217], v[74:77]
	v_mfma_f32_16x16x32_bf16 v[126:129], v[160:163], v[192:195], v[126:129]
	v_mfma_f32_16x16x32_bf16 v[122:125], v[168:171], v[192:195], v[122:125]
	v_mfma_f32_16x16x32_bf16 v[110:113], v[160:163], v[200:203], v[110:113]
	v_mfma_f32_16x16x32_bf16 v[106:109], v[168:171], v[200:203], v[106:109]
	v_mfma_f32_16x16x32_bf16 v[94:97], v[160:163], v[210:213], v[94:97]
	v_mfma_f32_16x16x32_bf16 v[90:93], v[168:171], v[210:213], v[90:93]
	v_mfma_f32_16x16x32_bf16 v[78:81], v[160:163], v[218:221], v[78:81]
	v_mfma_f32_16x16x32_bf16 v[74:77], v[168:171], v[218:221], v[74:77]
	v_mfma_f32_16x16x32_bf16 v[118:121], v[172:175], v[188:191], v[118:121]
	v_mfma_f32_16x16x32_bf16 v[114:117], v[180:183], v[188:191], v[114:117]
	v_mfma_f32_16x16x32_bf16 v[102:105], v[172:175], v[196:199], v[102:105]
	v_mfma_f32_16x16x32_bf16 v[98:101], v[180:183], v[196:199], v[98:101]
	v_mfma_f32_16x16x32_bf16 v[86:89], v[172:175], v[204:207], v[86:89]
	v_mfma_f32_16x16x32_bf16 v[82:85], v[180:183], v[204:207], v[82:85]
	v_mfma_f32_16x16x32_bf16 v[70:73], v[172:175], v[214:217], v[70:73]
	v_mfma_f32_16x16x32_bf16 v[66:69], v[180:183], v[214:217], v[66:69]
	v_mfma_f32_16x16x32_bf16 v[118:121], v[176:179], v[192:195], v[118:121]
	v_mfma_f32_16x16x32_bf16 v[114:117], v[184:187], v[192:195], v[114:117]
	v_mfma_f32_16x16x32_bf16 v[102:105], v[176:179], v[200:203], v[102:105]
	v_mfma_f32_16x16x32_bf16 v[98:101], v[184:187], v[200:203], v[98:101]
	v_mfma_f32_16x16x32_bf16 v[86:89], v[176:179], v[210:213], v[86:89]
	v_mfma_f32_16x16x32_bf16 v[82:85], v[184:187], v[210:213], v[82:85]
	v_mfma_f32_16x16x32_bf16 v[70:73], v[176:179], v[218:221], v[70:73]
	v_mfma_f32_16x16x32_bf16 v[66:69], v[184:187], v[218:221], v[66:69]
	s_setprio 0
	s_barrier
	s_add_i32 s0, s41, s31
	v_lshl_add_u64 v[222:223], s[26:27], 0, v[132:133]
	s_mov_b32 m0, s0
	ds_read_b128 v[188:191], v155 offset:16384
	ds_read_b128 v[192:195], v155 offset:17408
	ds_read_b128 v[196:199], v155 offset:18432
	ds_read_b128 v[200:203], v155 offset:19456
	ds_read_b128 v[204:207], v155 offset:20480
	ds_read_b128 v[210:213], v155 offset:21504
	ds_read_b128 v[214:217], v155 offset:22528
	ds_read_b128 v[218:221], v155 offset:23552
	global_load_lds_dwordx4 v[222:223], off
	s_add_i32 m0, s0, 0x2000
	s_add_u32 s0, s26, 0x40000
	v_lshl_add_u64 v[224:225], s[26:27], 0, v[136:137]
	s_addc_u32 s1, s27, 0
	s_add_i32 s55, s44, s31
	global_load_lds_dwordx4 v[224:225], off
	v_lshl_add_u64 v[226:227], s[0:1], 0, v[132:133]
	s_mov_b32 m0, s55
	v_lshl_add_u64 v[228:229], s[28:29], 0, v[134:135]
	global_load_lds_dwordx4 v[226:227], off
	v_lshl_add_u64 v[226:227], s[0:1], 0, v[136:137]
	s_add_i32 m0, s55, 0x2000
	s_nop 0
	global_load_lds_dwordx4 v[226:227], off
	v_lshl_add_u64 v[226:227], s[28:29], 0, v[130:131]
	s_mov_b32 m0, s34
	s_nop 0
	global_load_lds_dwordx4 v[226:227], off
	s_mov_b32 m0, s35
	s_nop 0
	global_load_lds_dwordx4 v[228:229], off
	s_waitcnt vmcnt(8)
	s_waitcnt lgkmcnt(0)
	s_barrier
; #define PG8_STAGE(bufoff, gbase, voff) do { _Pragma("unroll") for (int _i = 0; _i < 2; ++_i) \
;         __builtin_amdgcn_global_load_lds((const unsigned*)((const char*)(gbase) + (voff)[_i]), (PG8_LAS unsigned*)(lds + (bufoff) + ldsw + _i * 8192), 16, 0, 0); } while (0)
; #define PG8_LDA(dst, b, h) do { _Pragma("unroll") for (int m = 0; m < 4; ++m) _Pragma("unroll") for (int k = 0; k < 2; ++k) dst[m][k] = *(const PG8_LAS bf16x8*)(lds + PG8_SA(b, h) + aoff + m * 2048 + k * 1024); } while (0)
; #define PG8_LDB(dst, b, h) do { _Pragma("unroll") for (int n = 0; n < 2; ++n) _Pragma("unroll") for (int k = 0; k < 2; ++k) dst[n][k] = *(const PG8_LAS bf16x8*)(lds + PG8_SB(b, h) + boff + n * 2048 + k * 1024); } while (0)
; #define PG8_MMA(ai, bj, At, Bt) do { __builtin_amdgcn_s_setprio(1); _Pragma("unroll") for (int m = 0; m < 4; ++m) _Pragma("unroll") for (int n = 0; n < 2; ++n) _Pragma("unroll") for (int k = 0; k < 2; ++k) \
;         acc[ai][bj][m][n] = __builtin_amdgcn_mfma_f32_16x16x32_bf16(Bt[n][k], At[m][k], acc[ai][bj][m][n], 0, 0, 0); __builtin_amdgcn_s_setprio(0); } while (0)
; #define PG8_WAIT_V(n) asm volatile("s_waitcnt vmcnt(" #n ")" ::: "memory")
; #define PG8_WAIT_L(n) asm volatile("s_waitcnt lgkmcnt(" #n ")" ::: "memory")
; #define PG8_BAR __builtin_amdgcn_s_barrier()
; #define PG8_SCHED __builtin_amdgcn_sched_barrier(0)
; template <class Epi, class Sched, bool ALIGN_EPI = false, bool SP2 = false>
; __device__ __forceinline__ void gemm_phase(PG8_LAS unsigned char* lds, const Gemm g, const Sched& S, const Epi& E) {
;     ...
;             PG8_WAIT_V(8); PG8_WAIT_L(0); PG8_BAR; PG8_MMA(1, 0, At, B0); PG8_MMA(1, 1, At, B1); PG8_BAR; PG8_SCHED;
;             PG8_LDB(B0, 1, 0); PG8_LDB(B1, 1, 1); PG8_SCHED; PG8_LDA(At, 1, 0); PG8_STAGE(PG8_SA(0, 1), a2 + hstep, voffA);
;             PG8_WAIT_V(8); PG8_WAIT_L(0); PG8_BAR; PG8_MMA(0, 0, At, B0); PG8_MMA(0, 1, At, B1); PG8_BAR; PG8_SCHED;
	s_setprio 1
	s_waitcnt lgkmcnt(0)
	v_mfma_f32_16x16x32_bf16 v[62:65], v[146:149], v[188:191], v[62:65]
	v_mfma_f32_16x16x32_bf16 v[58:61], v[164:167], v[188:191], v[58:61]
	v_mfma_f32_16x16x32_bf16 v[46:49], v[146:149], v[196:199], v[46:49]
	v_mfma_f32_16x16x32_bf16 v[42:45], v[164:167], v[196:199], v[42:45]
	v_mfma_f32_16x16x32_bf16 v[30:33], v[146:149], v[204:207], v[30:33]
	v_mfma_f32_16x16x32_bf16 v[26:29], v[164:167], v[204:207], v[26:29]
	v_mfma_f32_16x16x32_bf16 v[14:17], v[146:149], v[214:217], v[14:17]
	v_mfma_f32_16x16x32_bf16 v[10:13], v[164:167], v[214:217], v[10:13]
	v_mfma_f32_16x16x32_bf16 v[62:65], v[160:163], v[192:195], v[62:65]
	v_mfma_f32_16x16x32_bf16 v[58:61], v[168:171], v[192:195], v[58:61]
	v_mfma_f32_16x16x32_bf16 v[46:49], v[160:163], v[200:203], v[46:49]
	v_mfma_f32_16x16x32_bf16 v[42:45], v[168:171], v[200:203], v[42:45]
	v_mfma_f32_16x16x32_bf16 v[30:33], v[160:163], v[210:213], v[30:33]
	v_mfma_f32_16x16x32_bf16 v[26:29], v[168:171], v[210:213], v[26:29]
	v_mfma_f32_16x16x32_bf16 v[14:17], v[160:163], v[218:221], v[14:17]
	v_mfma_f32_16x16x32_bf16 v[10:13], v[168:171], v[218:221], v[10:13]
	v_mfma_f32_16x16x32_bf16 v[54:57], v[172:175], v[188:191], v[54:57]
	v_mfma_f32_16x16x32_bf16 v[50:53], v[180:183], v[188:191], v[50:53]
	v_mfma_f32_16x16x32_bf16 v[38:41], v[172:175], v[196:199], v[38:41]
	v_mfma_f32_16x16x32_bf16 v[34:37], v[180:183], v[196:199], v[34:37]
	v_mfma_f32_16x16x32_bf16 v[22:25], v[172:175], v[204:207], v[22:25]
	v_mfma_f32_16x16x32_bf16 v[18:21], v[180:183], v[204:207], v[18:21]
	v_mfma_f32_16x16x32_bf16 v[6:9], v[172:175], v[214:217], v[6:9]
	v_mfma_f32_16x16x32_bf16 v[2:5], v[180:183], v[214:217], v[2:5]
	v_mfma_f32_16x16x32_bf16 v[54:57], v[176:179], v[192:195], v[54:57]
	v_mfma_f32_16x16x32_bf16 v[50:53], v[184:187], v[192:195], v[50:53]
	v_mfma_f32_16x16x32_bf16 v[38:41], v[176:179], v[200:203], v[38:41]
	v_mfma_f32_16x16x32_bf16 v[34:37], v[184:187], v[200:203], v[34:37]
	v_mfma_f32_16x16x32_bf16 v[22:25], v[176:179], v[210:213], v[22:25]
	v_mfma_f32_16x16x32_bf16 v[18:21], v[184:187], v[210:213], v[18:21]
	v_mfma_f32_16x16x32_bf16 v[6:9], v[176:179], v[218:221], v[6:9]
	v_mfma_f32_16x16x32_bf16 v[2:5], v[184:187], v[218:221], v[2:5]
	s_setprio 0
	s_barrier
	ds_read_b128 v[146:149], v157
	ds_read_b128 v[160:163], v157 offset:1024
	ds_read_b128 v[164:167], v157 offset:2048
	ds_read_b128 v[168:171], v157 offset:3072
	ds_read_b128 v[172:175], v158
	ds_read_b128 v[176:179], v158 offset:1024
	ds_read_b128 v[180:183], v158 offset:2048
	ds_read_b128 v[184:187], v158 offset:3072
	s_add_u32 s0, s28, 0x40000
	s_addc_u32 s1, s29, 0
	s_mov_b32 m0, s36
	v_lshl_add_u64 v[230:231], s[0:1], 0, v[130:131]
	ds_read_b128 v[188:191], v155 offset:32768
	ds_read_b128 v[192:195], v155 offset:33792
	ds_read_b128 v[196:199], v155 offset:34816
	ds_read_b128 v[200:203], v155 offset:35840
	ds_read_b128 v[204:207], v155 offset:36864
	ds_read_b128 v[210:213], v155 offset:37888
	ds_read_b128 v[214:217], v155 offset:38912
	ds_read_b128 v[218:221], v155 offset:39936
	global_load_lds_dwordx4 v[230:231], off
	v_lshl_add_u64 v[230:231], s[0:1], 0, v[134:135]
	s_mov_b32 m0, s37
	s_nop 0
	global_load_lds_dwordx4 v[230:231], off
	s_waitcnt vmcnt(8)
	s_waitcnt lgkmcnt(0)
	s_barrier
	s_setprio 1
	s_waitcnt lgkmcnt(0)
	v_mfma_f32_16x16x32_bf16 v[126:129], v[146:149], v[188:191], v[126:129]
	v_mfma_f32_16x16x32_bf16 v[122:125], v[164:167], v[188:191], v[122:125]
	v_mfma_f32_16x16x32_bf16 v[110:113], v[146:149], v[196:199], v[110:113]
	v_mfma_f32_16x16x32_bf16 v[106:109], v[164:167], v[196:199], v[106:109]
	v_mfma_f32_16x16x32_bf16 v[94:97], v[146:149], v[204:207], v[94:97]
	v_mfma_f32_16x16x32_bf16 v[90:93], v[164:167], v[204:207], v[90:93]
	v_mfma_f32_16x16x32_bf16 v[78:81], v[146:149], v[214:217], v[78:81]
	v_mfma_f32_16x16x32_bf16 v[74:77], v[164:167], v[214:217], v[74:77]
	v_mfma_f32_16x16x32_bf16 v[126:129], v[160:163], v[192:195], v[126:129]
	v_mfma_f32_16x16x32_bf16 v[122:125], v[168:171], v[192:195], v[122:125]
	v_mfma_f32_16x16x32_bf16 v[110:113], v[160:163], v[200:203], v[110:113]
	v_mfma_f32_16x16x32_bf16 v[106:109], v[168:171], v[200:203], v[106:109]
	v_mfma_f32_16x16x32_bf16 v[94:97], v[160:163], v[210:213], v[94:97]
	v_mfma_f32_16x16x32_bf16 v[90:93], v[168:171], v[210:213], v[90:93]
	v_mfma_f32_16x16x32_bf16 v[78:81], v[160:163], v[218:221], v[78:81]
	v_mfma_f32_16x16x32_bf16 v[74:77], v[168:171], v[218:221], v[74:77]
	v_mfma_f32_16x16x32_bf16 v[118:121], v[172:175], v[188:191], v[118:121]
	v_mfma_f32_16x16x32_bf16 v[114:117], v[180:183], v[188:191], v[114:117]
	v_mfma_f32_16x16x32_bf16 v[102:105], v[172:175], v[196:199], v[102:105]
	v_mfma_f32_16x16x32_bf16 v[98:101], v[180:183], v[196:199], v[98:101]
	v_mfma_f32_16x16x32_bf16 v[86:89], v[172:175], v[204:207], v[86:89]
	v_mfma_f32_16x16x32_bf16 v[82:85], v[180:183], v[204:207], v[82:85]
	v_mfma_f32_16x16x32_bf16 v[70:73], v[172:175], v[214:217], v[70:73]
	v_mfma_f32_16x16x32_bf16 v[66:69], v[180:183], v[214:217], v[66:69]
	v_mfma_f32_16x16x32_bf16 v[118:121], v[176:179], v[192:195], v[118:121]
	v_mfma_f32_16x16x32_bf16 v[114:117], v[184:187], v[192:195], v[114:117]
	v_mfma_f32_16x16x32_bf16 v[102:105], v[176:179], v[200:203], v[102:105]
	v_mfma_f32_16x16x32_bf16 v[98:101], v[184:187], v[200:203], v[98:101]
	v_mfma_f32_16x16x32_bf16 v[86:89], v[176:179], v[210:213], v[86:89]
	v_mfma_f32_16x16x32_bf16 v[82:85], v[184:187], v[210:213], v[82:85]
	v_mfma_f32_16x16x32_bf16 v[70:73], v[176:179], v[218:221], v[70:73]
	v_mfma_f32_16x16x32_bf16 v[66:69], v[184:187], v[218:221], v[66:69]
	s_setprio 0
	s_barrier
; #define PG8_STAGE(bufoff, gbase, voff) do { _Pragma("unroll") for (int _i = 0; _i < 2; ++_i) \
;         __builtin_amdgcn_global_load_lds((const unsigned*)((const char*)(gbase) + (voff)[_i]), (PG8_LAS unsigned*)(lds + (bufoff) + ldsw + _i * 8192), 16, 0, 0); } while (0)
; #define PG8_LDA(dst, b, h) do { _Pragma("unroll") for (int m = 0; m < 4; ++m) _Pragma("unroll") for (int k = 0; k < 2; ++k) dst[m][k] = *(const PG8_LAS bf16x8*)(lds + PG8_SA(b, h) + aoff + m * 2048 + k * 1024); } while (0)
; #define PG8_MMA(ai, bj, At, Bt) do { __builtin_amdgcn_s_setprio(1); _Pragma("unroll") for (int m = 0; m < 4; ++m) _Pragma("unroll") for (int n = 0; n < 2; ++n) _Pragma("unroll") for (int k = 0; k < 2; ++k) \
;         acc[ai][bj][m][n] = __builtin_amdgcn_mfma_f32_16x16x32_bf16(Bt[n][k], At[m][k], acc[ai][bj][m][n], 0, 0, 0); __builtin_amdgcn_s_setprio(0); } while (0)
; #define PG8_WAIT_V(n) asm volatile("s_waitcnt vmcnt(" #n ")" ::: "memory")
; #define PG8_WAIT_L(n) asm volatile("s_waitcnt lgkmcnt(" #n ")" ::: "memory")
; #define PG8_BAR __builtin_amdgcn_s_barrier()
; #define PG8_SCHED __builtin_amdgcn_sched_barrier(0)
; template <class Epi, class Sched, bool ALIGN_EPI = false, bool SP2 = false>
; __device__ __forceinline__ void gemm_phase(PG8_LAS unsigned char* lds, const Gemm g, const Sched& S, const Epi& E) {
;     ...
;             PG8_LDA(At, 1, 1); PG8_STAGE(PG8_SB(1, 0), b3, voffB); PG8_STAGE(PG8_SB(1, 1), b3 + hstep, voffB); PG8_STAGE(PG8_SA(1, 0), a3, voffA);
;             PG8_WAIT_V(8); PG8_WAIT_L(0); PG8_BAR; PG8_MMA(1, 0, At, B0); PG8_MMA(1, 1, At, B1); PG8_BAR; PG8_SCHED;
	s_add_i32 s0, s45, s31
	v_lshl_add_u64 v[222:223], v[222:223], 0, s[10:11]
	s_mov_b32 m0, s0
	ds_read_b128 v[188:191], v155 offset:49152
	ds_read_b128 v[192:195], v155 offset:50176
	ds_read_b128 v[196:199], v155 offset:51200
	ds_read_b128 v[200:203], v155 offset:52224
	ds_read_b128 v[204:207], v155 offset:53248
	ds_read_b128 v[210:213], v155 offset:54272
	ds_read_b128 v[214:217], v155 offset:55296
	ds_read_b128 v[218:221], v155 offset:56320
	global_load_lds_dwordx4 v[222:223], off
	s_add_i32 m0, s0, 0x2000
	s_add_u32 s0, s26, 0x40080
	v_lshl_add_u64 v[222:223], v[224:225], 0, s[10:11]
	s_addc_u32 s1, s27, 0
	s_add_i32 s26, s46, s31
	global_load_lds_dwordx4 v[222:223], off
	v_lshl_add_u64 v[222:223], s[0:1], 0, v[132:133]
	s_mov_b32 m0, s26
	s_nop 0
	global_load_lds_dwordx4 v[222:223], off
	v_lshl_add_u64 v[222:223], s[0:1], 0, v[136:137]
	s_add_i32 m0, s26, 0x2000
	s_nop 0
	global_load_lds_dwordx4 v[222:223], off
	v_lshl_add_u64 v[222:223], v[226:227], 0, s[10:11]
	s_mov_b32 m0, s38
	s_nop 0
	global_load_lds_dwordx4 v[222:223], off
	v_lshl_add_u64 v[222:223], v[228:229], 0, s[10:11]
	s_mov_b32 m0, s39
	s_nop 0
	global_load_lds_dwordx4 v[222:223], off
	s_waitcnt vmcnt(8)
	s_waitcnt lgkmcnt(0)
	s_barrier
	s_setprio 1
	s_waitcnt lgkmcnt(0)
	v_mfma_f32_16x16x32_bf16 v[62:65], v[146:149], v[188:191], v[62:65]
	v_mfma_f32_16x16x32_bf16 v[58:61], v[164:167], v[188:191], v[58:61]
	v_mfma_f32_16x16x32_bf16 v[46:49], v[146:149], v[196:199], v[46:49]
	v_mfma_f32_16x16x32_bf16 v[42:45], v[164:167], v[196:199], v[42:45]
	v_mfma_f32_16x16x32_bf16 v[30:33], v[146:149], v[204:207], v[30:33]
	v_mfma_f32_16x16x32_bf16 v[26:29], v[164:167], v[204:207], v[26:29]
	v_mfma_f32_16x16x32_bf16 v[14:17], v[146:149], v[214:217], v[14:17]
	v_mfma_f32_16x16x32_bf16 v[10:13], v[164:167], v[214:217], v[10:13]
	v_mfma_f32_16x16x32_bf16 v[62:65], v[160:163], v[192:195], v[62:65]
	v_mfma_f32_16x16x32_bf16 v[58:61], v[168:171], v[192:195], v[58:61]
	v_mfma_f32_16x16x32_bf16 v[46:49], v[160:163], v[200:203], v[46:49]
	v_mfma_f32_16x16x32_bf16 v[42:45], v[168:171], v[200:203], v[42:45]
	v_mfma_f32_16x16x32_bf16 v[30:33], v[160:163], v[210:213], v[30:33]
	v_mfma_f32_16x16x32_bf16 v[26:29], v[168:171], v[210:213], v[26:29]
	v_mfma_f32_16x16x32_bf16 v[14:17], v[160:163], v[218:221], v[14:17]
	v_mfma_f32_16x16x32_bf16 v[10:13], v[168:171], v[218:221], v[10:13]
	v_mfma_f32_16x16x32_bf16 v[54:57], v[172:175], v[188:191], v[54:57]
	v_mfma_f32_16x16x32_bf16 v[50:53], v[180:183], v[188:191], v[50:53]
	v_mfma_f32_16x16x32_bf16 v[38:41], v[172:175], v[196:199], v[38:41]
	v_mfma_f32_16x16x32_bf16 v[34:37], v[180:183], v[196:199], v[34:37]
	v_mfma_f32_16x16x32_bf16 v[22:25], v[172:175], v[204:207], v[22:25]
	v_mfma_f32_16x16x32_bf16 v[18:21], v[180:183], v[204:207], v[18:21]
	v_mfma_f32_16x16x32_bf16 v[6:9], v[172:175], v[214:217], v[6:9]
	v_mfma_f32_16x16x32_bf16 v[2:5], v[180:183], v[214:217], v[2:5]
	v_mfma_f32_16x16x32_bf16 v[54:57], v[176:179], v[192:195], v[54:57]
	v_mfma_f32_16x16x32_bf16 v[50:53], v[184:187], v[192:195], v[50:53]
	v_mfma_f32_16x16x32_bf16 v[38:41], v[176:179], v[200:203], v[38:41]
	v_mfma_f32_16x16x32_bf16 v[34:37], v[184:187], v[200:203], v[34:37]
	v_mfma_f32_16x16x32_bf16 v[22:25], v[176:179], v[210:213], v[22:25]
	v_mfma_f32_16x16x32_bf16 v[18:21], v[184:187], v[210:213], v[18:21]
	v_mfma_f32_16x16x32_bf16 v[6:9], v[176:179], v[218:221], v[6:9]
	v_mfma_f32_16x16x32_bf16 v[2:5], v[184:187], v[218:221], v[2:5]
	s_setprio 0
	s_barrier
	s_add_i32 s54, s54, 2
	s_add_u32 s4, s4, 0x100
	s_addc_u32 s5, s5, 0
	s_add_u32 s52, s52, 0x100
	s_addc_u32 s53, s53, 0
	s_cmp_gt_u32 s54, 13
	s_cbranch_scc0 .LBB0_1380
	s_and_b64 vcc, exec, s[12:13]
	s_cbranch_vccz .LBB0_1383
	s_barrier

; #define PG8_STAGE(bufoff, gbase, voff) do { _Pragma("unroll") for (int _i = 0; _i < 2; ++_i) \
;         __builtin_amdgcn_global_load_lds((const unsigned*)((const char*)(gbase) + (voff)[_i]), (PG8_LAS unsigned*)(lds + (bufoff) + ldsw + _i * 8192), 16, 0, 0); } while (0)
; #define PG8_LDA(dst, b, h) do { _Pragma("unroll") for (int m = 0; m < 4; ++m) _Pragma("unroll") for (int k = 0; k < 2; ++k) dst[m][k] = *(const PG8_LAS bf16x8*)(lds + PG8_SA(b, h) + aoff + m * 2048 + k * 1024); } while (0)
; #define PG8_LDB(dst, b, h) do { _Pragma("unroll") for (int n = 0; n < 2; ++n) _Pragma("unroll") for (int k = 0; k < 2; ++k) dst[n][k] = *(const PG8_LAS bf16x8*)(lds + PG8_SB(b, h) + boff + n * 2048 + k * 1024); } while (0)
; #define PG8_MMA(ai, bj, At, Bt) do { __builtin_amdgcn_s_setprio(1); _Pragma("unroll") for (int m = 0; m < 4; ++m) _Pragma("unroll") for (int n = 0; n < 2; ++n) _Pragma("unroll") for (int k = 0; k < 2; ++k) \
;         acc[ai][bj][m][n] = __builtin_amdgcn_mfma_f32_16x16x32_bf16(Bt[n][k], At[m][k], acc[ai][bj][m][n], 0, 0, 0); __builtin_amdgcn_s_setprio(0); } while (0)
; #define PG8_WAIT_V(n) asm volatile("s_waitcnt vmcnt(" #n ")" ::: "memory")
; #define PG8_WAIT_L(n) asm volatile("s_waitcnt lgkmcnt(" #n ")" ::: "memory")
; #define PG8_BAR __builtin_amdgcn_s_barrier()
; #define PG8_SCHED __builtin_amdgcn_sched_barrier(0)
; template <class Epi, class Sched, bool ALIGN_EPI = false, bool SP2 = false>
; __device__ __forceinline__ void gemm_phase(PG8_LAS unsigned char* lds, const Gemm g, const Sched& S, const Epi& E) {
;     ...
;             PG8_LDB(B0, 0, 0); PG8_LDB(B1, 0, 1); PG8_SCHED; PG8_LDA(At, 0, 0); PG8_STAGE(PG8_SA(1, 1), a1 + hstep, voffA);
;             PG8_WAIT_V(8); PG8_WAIT_L(0); PG8_BAR; PG8_MMA(0, 0, At, B0); PG8_MMA(0, 1, At, B1); PG8_BAR; PG8_SCHED;
;             PG8_LDA(At, 0, 1); PG8_STAGE(PG8_SB(0, 0), b2, voffB); PG8_STAGE(PG8_SB(0, 1), b2 + hstep, voffB); PG8_STAGE(PG8_SA(0, 0), a2, voffA);
;             PG8_WAIT_V(8); PG8_WAIT_L(0); PG8_BAR; PG8_MMA(1, 0, At, B0); PG8_MMA(1, 1, At, B1); PG8_BAR; PG8_SCHED;
.LBB0_1498:
	ds_read_b128 v[142:145], v148
	ds_read_b128 v[154:157], v148 offset:1024
	ds_read_b128 v[158:161], v148 offset:2048
	ds_read_b128 v[162:165], v148 offset:3072
	ds_read_b128 v[166:169], v149
	ds_read_b128 v[170:173], v149 offset:1024
	ds_read_b128 v[174:177], v149 offset:2048
	ds_read_b128 v[178:181], v149 offset:3072
	s_add_u32 s24, s22, 0x4000
	s_addc_u32 s25, s23, 0
	s_cmp_eq_u32 s47, 60
	s_cselect_b32 s27, s11, s25
	s_cselect_b32 s26, s43, s24
	s_cselect_b32 s25, s9, s46
	s_cselect_b32 s24, s44, s45
	v_lshl_add_u64 v[214:215], s[22:23], 0, v[136:137]
	s_add_i32 m0, s19, 0xc000
	ds_read_b128 v[182:185], v150
	ds_read_b128 v[186:189], v150 offset:1024
	ds_read_b128 v[190:193], v150 offset:2048
	ds_read_b128 v[194:197], v150 offset:3072
	ds_read_b128 v[198:201], v150 offset:4096
	ds_read_b128 v[202:205], v150 offset:5120
	ds_read_b128 v[206:209], v150 offset:6144
	ds_read_b128 v[210:213], v150 offset:7168
	global_load_lds_dwordx4 v[214:215], off
	v_lshl_add_u64 v[214:215], s[22:23], 0, v[138:139]
	s_add_i32 m0, s19, 0xe000
	s_nop 0
	global_load_lds_dwordx4 v[214:215], off
	s_waitcnt vmcnt(8)
	s_waitcnt lgkmcnt(0)
	s_barrier
	s_setprio 1
	s_waitcnt lgkmcnt(0)
	v_mfma_f32_16x16x32_bf16 v[124:127], v[142:145], v[182:185], v[124:127]
	v_mfma_f32_16x16x32_bf16 v[120:123], v[158:161], v[182:185], v[120:123]
	v_mfma_f32_16x16x32_bf16 v[108:111], v[142:145], v[190:193], v[108:111]
	v_mfma_f32_16x16x32_bf16 v[104:107], v[158:161], v[190:193], v[104:107]
	v_mfma_f32_16x16x32_bf16 v[92:95], v[142:145], v[198:201], v[92:95]
	v_mfma_f32_16x16x32_bf16 v[88:91], v[158:161], v[198:201], v[88:91]
	v_mfma_f32_16x16x32_bf16 v[76:79], v[142:145], v[206:209], v[76:79]
	v_mfma_f32_16x16x32_bf16 v[72:75], v[158:161], v[206:209], v[72:75]
	v_mfma_f32_16x16x32_bf16 v[124:127], v[154:157], v[186:189], v[124:127]
	v_mfma_f32_16x16x32_bf16 v[120:123], v[162:165], v[186:189], v[120:123]
	v_mfma_f32_16x16x32_bf16 v[108:111], v[154:157], v[194:197], v[108:111]
	v_mfma_f32_16x16x32_bf16 v[104:107], v[162:165], v[194:197], v[104:107]
	v_mfma_f32_16x16x32_bf16 v[92:95], v[154:157], v[202:205], v[92:95]
	v_mfma_f32_16x16x32_bf16 v[88:91], v[162:165], v[202:205], v[88:91]
	v_mfma_f32_16x16x32_bf16 v[76:79], v[154:157], v[210:213], v[76:79]
	v_mfma_f32_16x16x32_bf16 v[72:75], v[162:165], v[210:213], v[72:75]
	v_mfma_f32_16x16x32_bf16 v[116:119], v[166:169], v[182:185], v[116:119]
	v_mfma_f32_16x16x32_bf16 v[112:115], v[174:177], v[182:185], v[112:115]
	v_mfma_f32_16x16x32_bf16 v[100:103], v[166:169], v[190:193], v[100:103]
	v_mfma_f32_16x16x32_bf16 v[96:99], v[174:177], v[190:193], v[96:99]
	v_mfma_f32_16x16x32_bf16 v[84:87], v[166:169], v[198:201], v[84:87]
	v_mfma_f32_16x16x32_bf16 v[80:83], v[174:177], v[198:201], v[80:83]
	v_mfma_f32_16x16x32_bf16 v[68:71], v[166:169], v[206:209], v[68:71]
	v_mfma_f32_16x16x32_bf16 v[64:67], v[174:177], v[206:209], v[64:67]
	v_mfma_f32_16x16x32_bf16 v[116:119], v[170:173], v[186:189], v[116:119]
	v_mfma_f32_16x16x32_bf16 v[112:115], v[178:181], v[186:189], v[112:115]
	v_mfma_f32_16x16x32_bf16 v[100:103], v[170:173], v[194:197], v[100:103]
	v_mfma_f32_16x16x32_bf16 v[96:99], v[178:181], v[194:197], v[96:99]
	v_mfma_f32_16x16x32_bf16 v[84:87], v[170:173], v[202:205], v[84:87]
	v_mfma_f32_16x16x32_bf16 v[80:83], v[178:181], v[202:205], v[80:83]
	v_mfma_f32_16x16x32_bf16 v[68:71], v[170:173], v[210:213], v[68:71]
	v_mfma_f32_16x16x32_bf16 v[64:67], v[178:181], v[210:213], v[64:67]
	s_setprio 0
	s_barrier
	s_add_i32 s48, s37, s29
	v_lshl_add_u64 v[214:215], s[24:25], 0, v[130:131]
	s_mov_b32 m0, s48
	ds_read_b128 v[182:185], v150 offset:16384
	ds_read_b128 v[186:189], v150 offset:17408
	ds_read_b128 v[190:193], v150 offset:18432
	ds_read_b128 v[194:197], v150 offset:19456
	ds_read_b128 v[198:201], v150 offset:20480
	ds_read_b128 v[202:205], v150 offset:21504
	ds_read_b128 v[206:209], v150 offset:22528
	ds_read_b128 v[210:213], v150 offset:23552
	global_load_lds_dwordx4 v[214:215], off
	s_add_i32 m0, s48, 0x2000
	s_add_u32 s48, s24, 0x100000
	v_lshl_add_u64 v[216:217], s[24:25], 0, v[134:135]
	s_addc_u32 s49, s25, 0
	s_add_i32 s52, s38, s29
	global_load_lds_dwordx4 v[216:217], off
	v_lshl_add_u64 v[218:219], s[48:49], 0, v[130:131]
	s_mov_b32 m0, s52
	v_lshl_add_u64 v[220:221], s[26:27], 0, v[132:133]
	global_load_lds_dwordx4 v[218:219], off
	v_lshl_add_u64 v[218:219], s[48:49], 0, v[134:135]
	s_add_i32 m0, s52, 0x2000
	s_nop 0
	global_load_lds_dwordx4 v[218:219], off
	v_lshl_add_u64 v[218:219], s[26:27], 0, v[128:129]
	s_mov_b32 m0, s19
	s_nop 0
	global_load_lds_dwordx4 v[218:219], off
	s_mov_b32 m0, s21
	s_nop 0
	global_load_lds_dwordx4 v[220:221], off
	s_waitcnt vmcnt(8)
	s_waitcnt lgkmcnt(0)
	s_barrier
; #define PG8_STAGE(bufoff, gbase, voff) do { _Pragma("unroll") for (int _i = 0; _i < 2; ++_i) \
;         __builtin_amdgcn_global_load_lds((const unsigned*)((const char*)(gbase) + (voff)[_i]), (PG8_LAS unsigned*)(lds + (bufoff) + ldsw + _i * 8192), 16, 0, 0); } while (0)
; #define PG8_LDA(dst, b, h) do { _Pragma("unroll") for (int m = 0; m < 4; ++m) _Pragma("unroll") for (int k = 0; k < 2; ++k) dst[m][k] = *(const PG8_LAS bf16x8*)(lds + PG8_SA(b, h) + aoff + m * 2048 + k * 1024); } while (0)
; #define PG8_LDB(dst, b, h) do { _Pragma("unroll") for (int n = 0; n < 2; ++n) _Pragma("unroll") for (int k = 0; k < 2; ++k) dst[n][k] = *(const PG8_LAS bf16x8*)(lds + PG8_SB(b, h) + boff + n * 2048 + k * 1024); } while (0)
; #define PG8_MMA(ai, bj, At, Bt) do { __builtin_amdgcn_s_setprio(1); _Pragma("unroll") for (int m = 0; m < 4; ++m) _Pragma("unroll") for (int n = 0; n < 2; ++n) _Pragma("unroll") for (int k = 0; k < 2; ++k) \
;         acc[ai][bj][m][n] = __builtin_amdgcn_mfma_f32_16x16x32_bf16(Bt[n][k], At[m][k], acc[ai][bj][m][n], 0, 0, 0); __builtin_amdgcn_s_setprio(0); } while (0)
; #define PG8_WAIT_V(n) asm volatile("s_waitcnt vmcnt(" #n ")" ::: "memory")
; #define PG8_WAIT_L(n) asm volatile("s_waitcnt lgkmcnt(" #n ")" ::: "memory")
; #define PG8_BAR __builtin_amdgcn_s_barrier()
; #define PG8_SCHED __builtin_amdgcn_sched_barrier(0)
; template <class Epi, class Sched, bool ALIGN_EPI = false, bool SP2 = false>
; __device__ __forceinline__ void gemm_phase(PG8_LAS unsigned char* lds, const Gemm g, const Sched& S, const Epi& E) {
;     ...
;             PG8_WAIT_V(8); PG8_WAIT_L(0); PG8_BAR; PG8_MMA(0, 0, At, B0); PG8_MMA(0, 1, At, B1); PG8_BAR; PG8_SCHED;
;             PG8_LDA(At, 0, 1); PG8_STAGE(PG8_SB(0, 0), b2, voffB); PG8_STAGE(PG8_SB(0, 1), b2 + hstep, voffB); PG8_STAGE(PG8_SA(0, 0), a2, voffA);
;             PG8_WAIT_V(8); PG8_WAIT_L(0); PG8_BAR; PG8_MMA(1, 0, At, B0); PG8_MMA(1, 1, At, B1); PG8_BAR; PG8_SCHED;
;             PG8_LDB(B0, 1, 0); PG8_LDB(B1, 1, 1); PG8_SCHED; PG8_LDA(At, 1, 0); PG8_STAGE(PG8_SA(0, 1), a2 + hstep, voffA);
;             PG8_WAIT_V(8); PG8_WAIT_L(0); PG8_BAR; PG8_MMA(0, 0, At, B0); PG8_MMA(0, 1, At, B1); PG8_BAR; PG8_SCHED;
	s_setprio 1
	s_waitcnt lgkmcnt(0)
	v_mfma_f32_16x16x32_bf16 v[60:63], v[142:145], v[182:185], v[60:63]
	v_mfma_f32_16x16x32_bf16 v[56:59], v[158:161], v[182:185], v[56:59]
	v_mfma_f32_16x16x32_bf16 v[44:47], v[142:145], v[190:193], v[44:47]
	v_mfma_f32_16x16x32_bf16 v[40:43], v[158:161], v[190:193], v[40:43]
	v_mfma_f32_16x16x32_bf16 v[28:31], v[142:145], v[198:201], v[28:31]
	v_mfma_f32_16x16x32_bf16 v[24:27], v[158:161], v[198:201], v[24:27]
	v_mfma_f32_16x16x32_bf16 v[12:15], v[142:145], v[206:209], v[12:15]
	v_mfma_f32_16x16x32_bf16 v[8:11], v[158:161], v[206:209], v[8:11]
	v_mfma_f32_16x16x32_bf16 v[60:63], v[154:157], v[186:189], v[60:63]
	v_mfma_f32_16x16x32_bf16 v[56:59], v[162:165], v[186:189], v[56:59]
	v_mfma_f32_16x16x32_bf16 v[44:47], v[154:157], v[194:197], v[44:47]
	v_mfma_f32_16x16x32_bf16 v[40:43], v[162:165], v[194:197], v[40:43]
	v_mfma_f32_16x16x32_bf16 v[28:31], v[154:157], v[202:205], v[28:31]
	v_mfma_f32_16x16x32_bf16 v[24:27], v[162:165], v[202:205], v[24:27]
	v_mfma_f32_16x16x32_bf16 v[12:15], v[154:157], v[210:213], v[12:15]
	v_mfma_f32_16x16x32_bf16 v[8:11], v[162:165], v[210:213], v[8:11]
	v_mfma_f32_16x16x32_bf16 v[52:55], v[166:169], v[182:185], v[52:55]
	v_mfma_f32_16x16x32_bf16 v[48:51], v[174:177], v[182:185], v[48:51]
	v_mfma_f32_16x16x32_bf16 v[36:39], v[166:169], v[190:193], v[36:39]
	v_mfma_f32_16x16x32_bf16 v[32:35], v[174:177], v[190:193], v[32:35]
	v_mfma_f32_16x16x32_bf16 v[20:23], v[166:169], v[198:201], v[20:23]
	v_mfma_f32_16x16x32_bf16 v[16:19], v[174:177], v[198:201], v[16:19]
	v_mfma_f32_16x16x32_bf16 v[4:7], v[166:169], v[206:209], v[4:7]
	v_mfma_f32_16x16x32_bf16 v[0:3], v[174:177], v[206:209], v[0:3]
	v_mfma_f32_16x16x32_bf16 v[52:55], v[170:173], v[186:189], v[52:55]
	v_mfma_f32_16x16x32_bf16 v[48:51], v[178:181], v[186:189], v[48:51]
	v_mfma_f32_16x16x32_bf16 v[36:39], v[170:173], v[194:197], v[36:39]
	v_mfma_f32_16x16x32_bf16 v[32:35], v[178:181], v[194:197], v[32:35]
	v_mfma_f32_16x16x32_bf16 v[20:23], v[170:173], v[202:205], v[20:23]
	v_mfma_f32_16x16x32_bf16 v[16:19], v[178:181], v[202:205], v[16:19]
	v_mfma_f32_16x16x32_bf16 v[4:7], v[170:173], v[210:213], v[4:7]
	v_mfma_f32_16x16x32_bf16 v[0:3], v[178:181], v[210:213], v[0:3]
	s_setprio 0
	s_barrier
	ds_read_b128 v[142:145], v151
	ds_read_b128 v[154:157], v151 offset:1024
	ds_read_b128 v[158:161], v151 offset:2048
	ds_read_b128 v[162:165], v151 offset:3072
	ds_read_b128 v[166:169], v152
	ds_read_b128 v[170:173], v152 offset:1024
	ds_read_b128 v[174:177], v152 offset:2048
	ds_read_b128 v[178:181], v152 offset:3072
	s_add_u32 s26, s26, 0x4000
	s_addc_u32 s27, s27, 0
	s_mov_b32 m0, s31
	v_lshl_add_u64 v[222:223], s[26:27], 0, v[128:129]
	ds_read_b128 v[182:185], v150 offset:32768
	ds_read_b128 v[186:189], v150 offset:33792
	ds_read_b128 v[190:193], v150 offset:34816
	ds_read_b128 v[194:197], v150 offset:35840
	ds_read_b128 v[198:201], v150 offset:36864
	ds_read_b128 v[202:205], v150 offset:37888
	ds_read_b128 v[206:209], v150 offset:38912
	ds_read_b128 v[210:213], v150 offset:39936
	global_load_lds_dwordx4 v[222:223], off
	v_lshl_add_u64 v[222:223], s[26:27], 0, v[132:133]
	s_mov_b32 m0, s33
	s_nop 0
	global_load_lds_dwordx4 v[222:223], off
	s_waitcnt vmcnt(8)
	s_waitcnt lgkmcnt(0)
	s_barrier
	s_setprio 1
	s_waitcnt lgkmcnt(0)
	v_mfma_f32_16x16x32_bf16 v[124:127], v[142:145], v[182:185], v[124:127]
	v_mfma_f32_16x16x32_bf16 v[120:123], v[158:161], v[182:185], v[120:123]
	v_mfma_f32_16x16x32_bf16 v[108:111], v[142:145], v[190:193], v[108:111]
	v_mfma_f32_16x16x32_bf16 v[104:107], v[158:161], v[190:193], v[104:107]
	v_mfma_f32_16x16x32_bf16 v[92:95], v[142:145], v[198:201], v[92:95]
	v_mfma_f32_16x16x32_bf16 v[88:91], v[158:161], v[198:201], v[88:91]
	v_mfma_f32_16x16x32_bf16 v[76:79], v[142:145], v[206:209], v[76:79]
	v_mfma_f32_16x16x32_bf16 v[72:75], v[158:161], v[206:209], v[72:75]
	v_mfma_f32_16x16x32_bf16 v[124:127], v[154:157], v[186:189], v[124:127]
	v_mfma_f32_16x16x32_bf16 v[120:123], v[162:165], v[186:189], v[120:123]
	v_mfma_f32_16x16x32_bf16 v[108:111], v[154:157], v[194:197], v[108:111]
	v_mfma_f32_16x16x32_bf16 v[104:107], v[162:165], v[194:197], v[104:107]
	v_mfma_f32_16x16x32_bf16 v[92:95], v[154:157], v[202:205], v[92:95]
	v_mfma_f32_16x16x32_bf16 v[88:91], v[162:165], v[202:205], v[88:91]
	v_mfma_f32_16x16x32_bf16 v[76:79], v[154:157], v[210:213], v[76:79]
	v_mfma_f32_16x16x32_bf16 v[72:75], v[162:165], v[210:213], v[72:75]
	v_mfma_f32_16x16x32_bf16 v[116:119], v[166:169], v[182:185], v[116:119]
	v_mfma_f32_16x16x32_bf16 v[112:115], v[174:177], v[182:185], v[112:115]
	v_mfma_f32_16x16x32_bf16 v[100:103], v[166:169], v[190:193], v[100:103]
	v_mfma_f32_16x16x32_bf16 v[96:99], v[174:177], v[190:193], v[96:99]
	v_mfma_f32_16x16x32_bf16 v[84:87], v[166:169], v[198:201], v[84:87]
	v_mfma_f32_16x16x32_bf16 v[80:83], v[174:177], v[198:201], v[80:83]
	v_mfma_f32_16x16x32_bf16 v[68:71], v[166:169], v[206:209], v[68:71]
	v_mfma_f32_16x16x32_bf16 v[64:67], v[174:177], v[206:209], v[64:67]
	v_mfma_f32_16x16x32_bf16 v[116:119], v[170:173], v[186:189], v[116:119]
	v_mfma_f32_16x16x32_bf16 v[112:115], v[178:181], v[186:189], v[112:115]
	v_mfma_f32_16x16x32_bf16 v[100:103], v[170:173], v[194:197], v[100:103]
	v_mfma_f32_16x16x32_bf16 v[96:99], v[178:181], v[194:197], v[96:99]
	v_mfma_f32_16x16x32_bf16 v[84:87], v[170:173], v[202:205], v[84:87]
	v_mfma_f32_16x16x32_bf16 v[80:83], v[178:181], v[202:205], v[80:83]
	v_mfma_f32_16x16x32_bf16 v[68:71], v[170:173], v[210:213], v[68:71]
	v_mfma_f32_16x16x32_bf16 v[64:67], v[178:181], v[210:213], v[64:67]
	s_setprio 0
	s_barrier
; #define PG8_STAGE(bufoff, gbase, voff) do { _Pragma("unroll") for (int _i = 0; _i < 2; ++_i) \
;         __builtin_amdgcn_global_load_lds((const unsigned*)((const char*)(gbase) + (voff)[_i]), (PG8_LAS unsigned*)(lds + (bufoff) + ldsw + _i * 8192), 16, 0, 0); } while (0)
; #define PG8_LDA(dst, b, h) do { _Pragma("unroll") for (int m = 0; m < 4; ++m) _Pragma("unroll") for (int k = 0; k < 2; ++k) dst[m][k] = *(const PG8_LAS bf16x8*)(lds + PG8_SA(b, h) + aoff + m * 2048 + k * 1024); } while (0)
; #define PG8_MMA(ai, bj, At, Bt) do { __builtin_amdgcn_s_setprio(1); _Pragma("unroll") for (int m = 0; m < 4; ++m) _Pragma("unroll") for (int n = 0; n < 2; ++n) _Pragma("unroll") for (int k = 0; k < 2; ++k) \
;         acc[ai][bj][m][n] = __builtin_amdgcn_mfma_f32_16x16x32_bf16(Bt[n][k], At[m][k], acc[ai][bj][m][n], 0, 0, 0); __builtin_amdgcn_s_setprio(0); } while (0)
; #define PG8_WAIT_V(n) asm volatile("s_waitcnt vmcnt(" #n ")" ::: "memory")
; #define PG8_WAIT_L(n) asm volatile("s_waitcnt lgkmcnt(" #n ")" ::: "memory")
; #define PG8_BAR __builtin_amdgcn_s_barrier()
; #define PG8_SCHED __builtin_amdgcn_sched_barrier(0)
; template <class Epi, class Sched, bool ALIGN_EPI = false, bool SP2 = false>
; __device__ __forceinline__ void gemm_phase(PG8_LAS unsigned char* lds, const Gemm g, const Sched& S, const Epi& E) {
;     ...
;             PG8_LDA(At, 1, 1); PG8_STAGE(PG8_SB(1, 0), b3, voffB); PG8_STAGE(PG8_SB(1, 1), b3 + hstep, voffB); PG8_STAGE(PG8_SA(1, 0), a3, voffA);
;             PG8_WAIT_V(8); PG8_WAIT_L(0); PG8_BAR; PG8_MMA(1, 0, At, B0); PG8_MMA(1, 1, At, B1); PG8_BAR; PG8_SCHED;
	s_add_i32 s26, s39, s29
	v_lshl_add_u64 v[214:215], v[214:215], 0, s[4:5]
	s_mov_b32 m0, s26
	ds_read_b128 v[182:185], v150 offset:49152
	ds_read_b128 v[186:189], v150 offset:50176
	ds_read_b128 v[190:193], v150 offset:51200
	ds_read_b128 v[194:197], v150 offset:52224
	ds_read_b128 v[198:201], v150 offset:53248
	ds_read_b128 v[202:205], v150 offset:54272
	ds_read_b128 v[206:209], v150 offset:55296
	ds_read_b128 v[210:213], v150 offset:56320
	global_load_lds_dwordx4 v[214:215], off
	s_add_i32 m0, s26, 0x2000
	s_add_u32 s24, s24, 0x100080
	v_lshl_add_u64 v[214:215], v[216:217], 0, s[4:5]
	s_addc_u32 s25, s25, 0
	s_add_i32 s26, s40, s29
	global_load_lds_dwordx4 v[214:215], off
	v_lshl_add_u64 v[214:215], s[24:25], 0, v[130:131]
	s_mov_b32 m0, s26
	s_nop 0
	global_load_lds_dwordx4 v[214:215], off
	v_lshl_add_u64 v[214:215], s[24:25], 0, v[134:135]
	s_add_i32 m0, s26, 0x2000
	s_nop 0
	global_load_lds_dwordx4 v[214:215], off
	v_lshl_add_u64 v[214:215], v[218:219], 0, s[70:71]
	s_mov_b32 m0, s34
	s_nop 0
	global_load_lds_dwordx4 v[214:215], off
	v_lshl_add_u64 v[214:215], v[220:221], 0, s[70:71]
	s_mov_b32 m0, s35
	s_nop 0
	global_load_lds_dwordx4 v[214:215], off
	s_waitcnt vmcnt(8)
	s_waitcnt lgkmcnt(0)
	s_barrier
	s_setprio 1
	s_waitcnt lgkmcnt(0)
	v_mfma_f32_16x16x32_bf16 v[60:63], v[142:145], v[182:185], v[60:63]
	v_mfma_f32_16x16x32_bf16 v[56:59], v[158:161], v[182:185], v[56:59]
	v_mfma_f32_16x16x32_bf16 v[44:47], v[142:145], v[190:193], v[44:47]
	v_mfma_f32_16x16x32_bf16 v[40:43], v[158:161], v[190:193], v[40:43]
	v_mfma_f32_16x16x32_bf16 v[28:31], v[142:145], v[198:201], v[28:31]
	v_mfma_f32_16x16x32_bf16 v[24:27], v[158:161], v[198:201], v[24:27]
	v_mfma_f32_16x16x32_bf16 v[12:15], v[142:145], v[206:209], v[12:15]
	v_mfma_f32_16x16x32_bf16 v[8:11], v[158:161], v[206:209], v[8:11]
	v_mfma_f32_16x16x32_bf16 v[60:63], v[154:157], v[186:189], v[60:63]
	v_mfma_f32_16x16x32_bf16 v[56:59], v[162:165], v[186:189], v[56:59]
	v_mfma_f32_16x16x32_bf16 v[44:47], v[154:157], v[194:197], v[44:47]
	v_mfma_f32_16x16x32_bf16 v[40:43], v[162:165], v[194:197], v[40:43]
	v_mfma_f32_16x16x32_bf16 v[28:31], v[154:157], v[202:205], v[28:31]
	v_mfma_f32_16x16x32_bf16 v[24:27], v[162:165], v[202:205], v[24:27]
	v_mfma_f32_16x16x32_bf16 v[12:15], v[154:157], v[210:213], v[12:15]
	v_mfma_f32_16x16x32_bf16 v[8:11], v[162:165], v[210:213], v[8:11]
	v_mfma_f32_16x16x32_bf16 v[52:55], v[166:169], v[182:185], v[52:55]
	v_mfma_f32_16x16x32_bf16 v[48:51], v[174:177], v[182:185], v[48:51]
	v_mfma_f32_16x16x32_bf16 v[36:39], v[166:169], v[190:193], v[36:39]
	v_mfma_f32_16x16x32_bf16 v[32:35], v[174:177], v[190:193], v[32:35]
	v_mfma_f32_16x16x32_bf16 v[20:23], v[166:169], v[198:201], v[20:23]
	v_mfma_f32_16x16x32_bf16 v[16:19], v[174:177], v[198:201], v[16:19]
	v_mfma_f32_16x16x32_bf16 v[4:7], v[166:169], v[206:209], v[4:7]
	v_mfma_f32_16x16x32_bf16 v[0:3], v[174:177], v[206:209], v[0:3]
	v_mfma_f32_16x16x32_bf16 v[52:55], v[170:173], v[186:189], v[52:55]
	v_mfma_f32_16x16x32_bf16 v[48:51], v[178:181], v[186:189], v[48:51]
	v_mfma_f32_16x16x32_bf16 v[36:39], v[170:173], v[194:197], v[36:39]
	v_mfma_f32_16x16x32_bf16 v[32:35], v[178:181], v[194:197], v[32:35]
	v_mfma_f32_16x16x32_bf16 v[20:23], v[170:173], v[202:205], v[20:23]
	v_mfma_f32_16x16x32_bf16 v[16:19], v[178:181], v[202:205], v[16:19]
	v_mfma_f32_16x16x32_bf16 v[4:7], v[170:173], v[210:213], v[4:7]
	v_mfma_f32_16x16x32_bf16 v[0:3], v[178:181], v[210:213], v[0:3]
	s_setprio 0
	s_barrier
	s_add_i32 s47, s47, 2
	s_add_u32 s22, s22, 0x10000
	s_addc_u32 s23, s23, 0
	s_add_u32 s45, s45, 0x100
	s_addc_u32 s46, s46, 0
	s_cmp_gt_u32 s47, 61
	s_cbranch_scc0 .LBB0_1498
	s_and_b64 vcc, exec, s[6:7]
	s_cbranch_vccz .LBB0_1501
	s_barrier
